# SSD part 1: state MFMAs computed transposed (A/B swapped) so STATES is written with 4 dwordx4 stores per combo instead of 16 dword stores
# baseline (speedup 1.0000x reference)
; #define LAS __attribute__((address_space(3)))
; DI void ssd_part1_unit(int u, const bf16* PROJ, float* DT, const bf16* H, const bf16* wdtb_l, const float* dt_bias_l, const float* cw, const float* cb, const float* a_log_l, float* STATES, float* TOT,
;                        LAS unsigned char* ldsu, int tid, int wave, int lane) {
;     const int b = u >> 5, c = (u >> 1) & 15, grp = u & 1, t0 = c * 128;
;     LAS char* lds = (LAS char*)ldsu;
;     LAS char* XS = lds; LAS char* BM = lds + IMG_BYTES;
;     LAS float* gtab = (LAS float*)(lds + 3 * IMG_BYTES); LAS float* wtab = gtab + 512;
;     const int r = lane & 15, g = lane >> 4, q = (lane & 15) >> 2, p = lane & 3;
;     __syncthreads();
;     {
;         LAS char* wl = lds + 3 * IMG_BYTES + 4096;
;     ...
;     bf16x8 bfr[4];
; #pragma unroll
;     for (int ks = 0; ks < 4; ++ks) { const LAS char* bp = BM + (32 * ks + 8 * g + q) * IMG_PITCH + 32 * wave + 8 * p; bfr[ks] = cat8(vtr(bp), vtr(bp + 4 * IMG_PITCH)); }
; #pragma unroll
;     for (int combo = 0; combo < 4; ++combo) {
;         const int hh = combo >> 1, dir = combo & 1, h = 2 * grp + hh;
;         f32x4 acc[4];
; #pragma unroll
;         for (int pt = 0; pt < 4; ++pt) acc[pt] = (f32x4){0.f, 0.f, 0.f, 0.f};
; #pragma unroll
;         for (int ks = 0; ks < 4; ++ks) {
;             const f32x4 w0 = *(const LAS f32x4*)(wtab + combo * 128 + 32 * ks + 8 * g), w1 = *(const LAS f32x4*)(wtab + combo * 128 + 32 * ks + 8 * g + 4);
; #pragma unroll
;             for (int pt = 0; pt < 4; ++pt) {
;                 const LAS char* xp = XS + (32 * ks + 8 * g + q) * IMG_PITCH + (hh * 64 + 16 * pt) * 2 + 8 * p;
;                 const u32x2 lo = __builtin_bit_cast(u32x2, vtr(xp)), hi = __builtin_bit_cast(u32x2, vtr(xp + 4 * IMG_PITCH));
;                 u32x4 af; af.x = pk2(bflo(lo.x) * w0[0], bfhi(lo.x) * w0[1]); af.y = pk2(bflo(lo.y) * w0[2], bfhi(lo.y) * w0[3]);
;                 af.z = pk2(bflo(hi.x) * w1[0], bfhi(hi.x) * w1[1]); af.w = pk2(bflo(hi.y) * w1[2], bfhi(hi.y) * w1[3]);
;                 acc[pt] = MFMA16(__builtin_bit_cast(bf16x8, af), bfr[ks], acc[pt]);
;             }
;         }
;         float* sb = STATES + ((size_t)(((b * 16 + c) * 4 + h) * 2 + dir) * 64) * 128;
; #pragma unroll
;         for (int pt = 0; pt < 4; ++pt)
; #pragma unroll
;             for (int i = 0; i < 4; ++i) sb[(size_t)(16 * pt + 4 * g + i) * 128 + 16 * wave + r] = acc[pt][i];
.LBB0_262:
	v_readlane_b32 s0, v253, 0
	s_waitcnt vmcnt(0)
	s_barrier
	v_mbcnt_lo_u32_b32 v4, -1, 0
	v_mbcnt_hi_u32_b32 v4, -1, v4
	s_and_b64 vcc, exec, s[36:37]
	v_add_u32_e32 v103, s0, v4
	v_readlane_b32 s56, v255, 10
	v_readfirstlane_b32 s0, v103
	s_barrier
	s_cbranch_vccnz .LBB0_356
	v_readlane_b32 s30, v255, 27
	s_lshl_b32 s34, s30, 3
	v_readlane_b32 s44, v253, 5
	s_ashr_i32 s1, s0, 6
	s_lshl_b64 s[4:5], s[34:35], 2
	v_readlane_b32 s50, v253, 11
	v_readlane_b32 s51, v253, 12
	s_add_u32 s40, s50, s4
	s_mul_i32 s34, s30, 0xf00
	s_addc_u32 s41, s51, s5
	s_lshl_b64 s[20:21], s[34:35], 2
	v_readlane_b32 s45, v253, 6
	s_add_u32 s20, s44, s20
	s_mul_i32 s34, s30, 0x300
	v_readlane_b32 s46, v253, 7
	s_addc_u32 s21, s45, s21
	s_lshl_b64 s[26:27], s[34:35], 2
	v_readlane_b32 s47, v253, 8
	s_add_u32 s26, s46, s26
	v_readlane_b32 s48, v253, 9
	s_addc_u32 s27, s47, s27
	v_readlane_b32 s49, v253, 10
	s_add_u32 s2, s48, s4
	s_addc_u32 s4, s49, s5
	s_mul_i32 s5, s1, 0x1100
	s_add_i32 s5, s5, 0
	s_movk_i32 s16, 0x400
	s_add_i32 s5, s5, 0x11000
	v_cmp_gt_i32_e64 s[36:37], s16, v103
	s_lshl_b32 s16, s30, 15
	v_readlane_b32 s30, v253, 46
	v_readlane_b32 s31, v255, 28
	s_add_u32 s30, s30, s16
	v_readlane_b32 s16, v253, 47
	v_lshlrev_b32_e32 v6, 4, v103
	s_addc_u32 s31, s16, 0
	v_and_b32_e32 v188, 0x7f0, v6
	v_readlane_b32 s16, v255, 13
	v_lshlrev_b32_e32 v8, 4, v4
	v_lshl_add_u64 v[100:101], s[30:31], 0, v[188:189]
	v_add_u32_e32 v102, s16, v188
	v_and_b32_e32 v188, 0xf0, v8
	v_and_b32_e32 v7, 15, v4
	s_lshl_b32 s30, s1, 4
	v_readlane_b32 s38, v254, 52
	v_add_u32_e32 v13, s5, v188
	v_mov_b32_e32 v14, s5
	s_movk_i32 s5, 0x110
	v_readlane_b32 s39, v254, 53
	v_mad_u32_u24 v15, v7, s5, v14
	v_mov_b32_e32 v14, s16
	v_readlane_b32 s5, v255, 14
	s_cmp_lt_i32 s1, 4
	v_lshl_add_u64 v[104:105], s[38:39], 0, v[188:189]
	v_mad_u32_u24 v19, v7, s93, v14
	v_lshlrev_b32_e32 v188, 2, v7
	v_mov_b32_e32 v14, s5
	s_movk_i32 s5, 0x100
	s_cselect_b64 s[96:97], -1, 0
	s_and_b32 s16, s1, 1
	v_lshl_add_u64 v[106:107], s[40:41], 0, v[188:189]
	v_readlane_b32 s42, v253, 44
	v_cmp_gt_u32_e64 s[40:41], s5, v103
	s_ashr_i32 s5, s0, 7
	s_lshl_b32 s33, s16, 2
	s_lshl_b32 s0, s16, 4
	v_and_b32_e32 v5, 63, v4
	v_readlane_b32 s43, v253, 45
	s_add_u32 s94, s42, s0
	v_readlane_b32 s52, v253, 13
	v_readlane_b32 s53, v253, 14
	v_lshlrev_b32_e32 v11, 3, v5
	s_addc_u32 s95, s43, 0
	v_readlane_b32 s54, v253, 15
	v_readlane_b32 s55, v253, 16
	v_lshl_add_u64 v[108:109], s[42:43], 0, v[188:189]
	v_lshlrev_b32_e32 v110, 1, v5
	v_cmp_eq_u32_e64 s[42:43], 0, v5
	v_cmp_gt_u32_e64 s[44:45], 2, v5
	v_cmp_gt_u32_e64 s[46:47], 4, v5
	v_cmp_gt_u32_e64 s[48:49], 8, v5
	v_cmp_gt_u32_e64 s[50:51], 16, v5
	v_cmp_gt_u32_e64 s[52:53], 32, v5
	s_cmp_eq_u32 s16, 0
	v_lshl_or_b32 v5, s1, 9, v11
	v_readlane_b32 s0, v255, 15
	s_cselect_b64 s[54:55], -1, 0
	s_lshl_b32 s1, s1, 5
	v_add_u32_e32 v229, s0, v5
	s_add_i32 s0, 0, 0x1a000
	v_bfe_u32 v9, v4, 4, 2
	v_lshlrev_b32_e32 v6, 6, v4
	v_and_b32_e32 v17, 48, v4
	v_add_u32_e32 v230, s0, v5
	v_bfe_u32 v4, v4, 2, 2
	s_add_i32 s1, s1, 0
	v_and_b32_e32 v5, 24, v11
	s_ashr_i32 s31, s30, 31
	v_cndmask_b32_e64 v16, v14, 0, s[40:41]
	v_lshrrev_b32_e32 v14, 1, v103
	v_add_u32_e32 v11, s1, v5
	v_lshl_or_b32 v4, v9, 3, v4
	v_lshl_add_u32 v231, v9, 5, s0
	s_lshl_b64 s[0:1], s[30:31], 2
	v_readlane_b32 s58, v253, 19
	v_readlane_b32 s59, v253, 20
	v_and_b32_e32 v6, 0xc00, v6
	v_lshlrev_b32_e32 v191, 3, v7
	v_and_b32_e32 v225, 0x78, v14
	v_mul_u32_u24_e32 v25, 0x110, v4
	v_lshlrev_b32_e32 v4, 9, v9
	s_add_u32 s0, s12, s0
	v_readlane_b32 s56, v253, 17
	v_readlane_b32 s58, v253, 24
	v_or_b32_e32 v8, 0x1000, v6
	v_or_b32_e32 v10, 0x2000, v6
	v_or_b32_e32 v12, 0x3000, v6
	v_cmp_gt_u32_e64 s[38:39], 8, v7
	v_mul_u32_u24_e32 v21, 0x110, v9
	v_and_b32_e32 v14, 56, v191
	v_lshl_add_u32 v7, v7, 4, v16
	v_mul_u32_u24_e32 v23, 0x110, v225
	s_addc_u32 s1, s13, s1
	v_or_b32_e32 v16, 0x1800, v4
	v_or_b32_e32 v18, 0x800, v4
	v_or_b32_e32 v20, 0x880, v4
	v_or_b32_e32 v22, 0x900, v4
	v_or_b32_e32 v24, 0x980, v4
	v_or_b32_e32 v26, 0x1000, v4
	v_or_b32_e32 v28, 0x1080, v4
	v_or_b32_e32 v30, 0x1100, v4
	v_or_b32_e32 v32, 0x1180, v4
	v_or_b32_e32 v34, 0x1880, v4
	v_or_b32_e32 v36, 0x1900, v4
	v_or_b32_e32 v38, 0x1980, v4
	v_readlane_b32 s59, v253, 25
	v_readlane_b32 s56, v255, 10
	v_lshlrev_b32_e32 v111, 2, v9
	v_add_u32_e32 v228, -2, v225
	v_lshl_add_u64 v[112:113], s[0:1], 0, v[188:189]
	v_add3_u32 v232, 0, v5, v25
	v_lshlrev_b32_e32 v114, 1, v6
	v_lshlrev_b32_e32 v188, 1, v8
	v_lshlrev_b32_e32 v116, 1, v10
	v_lshlrev_b32_e32 v118, 1, v12
	v_lshlrev_b32_e32 v120, 1, v14
	v_add_u32_e32 v242, v7, v23
	v_add_u32_e32 v243, v11, v25
	v_lshlrev_b32_e32 v122, 2, v4
	v_and_b32_e32 v124, 15, v103
	v_mul_u32_u24_e32 v124, 0x1fc, v124
	v_lshl_add_u32 v124, v9, 4, v124
	v_add_u32_e32 v126, 0x2000, v124
	v_add_u32_e32 v128, 0x4000, v124
	v_add_u32_e32 v130, 0x6000, v124
	v_add_u32_e32 v244, v13, v21
	v_add_u32_e32 v245, v15, v17
	v_add_u32_e32 v246, v19, v17
	s_mov_b32 s31, s66
	v_readlane_b32 s57, v253, 18
	s_branch .LBB0_266

; #define LAS __attribute__((address_space(3)))
; #define MFMA16(a, b, c) __builtin_amdgcn_mfma_f32_16x16x32_bf16((a), (b), (c), 0, 0, 0)
; DI unsigned pk2(float lo, float hi) { f32x2_t v = {lo, hi}; bf16x2_t b = __builtin_convertvector(v, bf16x2_t); return __builtin_bit_cast(unsigned, b); }
; DI s16x4 vtr(const LAS char* p) { return __builtin_bit_cast(s16x4, __builtin_amdgcn_ds_read_tr16_b64_v4i16((LAS s16x4*)p)); }
; DI void ssd_part1_unit(int u, const bf16* PROJ, float* DT, const bf16* H, const bf16* wdtb_l, const float* dt_bias_l, const float* cw, const float* cb, const float* a_log_l, float* STATES, float* TOT,
;                        LAS unsigned char* ldsu, int tid, int wave, int lane) {
;     ...
; #pragma unroll
;     for (int combo = 0; combo < 4; ++combo) {
;         const int hh = combo >> 1, dir = combo & 1, h = 2 * grp + hh;
;         f32x4 acc[4];
; #pragma unroll
;         for (int pt = 0; pt < 4; ++pt) acc[pt] = (f32x4){0.f, 0.f, 0.f, 0.f};
; #pragma unroll
;         for (int ks = 0; ks < 4; ++ks) {
;             const f32x4 w0 = *(const LAS f32x4*)(wtab + combo * 128 + 32 * ks + 8 * g), w1 = *(const LAS f32x4*)(wtab + combo * 128 + 32 * ks + 8 * g + 4);
; #pragma unroll
;             for (int pt = 0; pt < 4; ++pt) {
;                 const LAS char* xp = XS + (32 * ks + 8 * g + q) * IMG_PITCH + (hh * 64 + 16 * pt) * 2 + 8 * p;
;                 const u32x2 lo = __builtin_bit_cast(u32x2, vtr(xp)), hi = __builtin_bit_cast(u32x2, vtr(xp + 4 * IMG_PITCH));
;                 u32x4 af; af.x = pk2(bflo(lo.x) * w0[0], bfhi(lo.x) * w0[1]); af.y = pk2(bflo(lo.y) * w0[2], bfhi(lo.y) * w0[3]);
;                 af.z = pk2(bflo(hi.x) * w1[0], bfhi(hi.x) * w1[1]); af.w = pk2(bflo(hi.y) * w1[2], bfhi(hi.y) * w1[3]);
;                 acc[pt] = MFMA16(__builtin_bit_cast(bf16x8, af), bfr[ks], acc[pt]);
;             }
;         }
;         float* sb = STATES + ((size_t)(((b * 16 + c) * 4 + h) * 2 + dir) * 64) * 128;
; #pragma unroll
;         for (int pt = 0; pt < 4; ++pt)
; #pragma unroll
;             for (int i = 0; i < 4; ++i) sb[(size_t)(16 * pt + 4 * g + i) * 128 + 16 * wave + r] = acc[pt][i];
.LBB0_265:
	s_waitcnt lgkmcnt(0)
	s_barrier
	ds_read_b64_tr_b16 v[16:17], v243 offset:34816
	ds_read_b64_tr_b16 v[18:19], v243 offset:35904
	ds_read_b64_tr_b16 v[12:13], v243 offset:43520
	ds_read_b64_tr_b16 v[14:15], v243 offset:44608
	ds_read_b64_tr_b16 v[8:9], v243 offset:52224
	ds_read_b64_tr_b16 v[10:11], v243 offset:53312
	ds_read_b64_tr_b16 v[4:5], v243 offset:60928
	ds_read_b64_tr_b16 v[6:7], v243 offset:62016
	ds_read_b128 v[28:31], v231
	ds_read_b128 v[24:27], v231 offset:16
	ds_read_b64_tr_b16 v[22:23], v232 offset:1088
	ds_read_b64_tr_b16 v[20:21], v232
	ds_read_b64_tr_b16 v[32:33], v232 offset:32
	s_lshl_b32 s0, s62, 6
	s_lshl_b32 s1, s34, 2
	s_waitcnt lgkmcnt(2)
	v_lshlrev_b32_e32 v64, 16, v22
	s_waitcnt lgkmcnt(1)
	v_lshlrev_b32_e32 v58, 16, v20
	v_and_b32_e32 v59, 0xffff0000, v20
	v_pk_mul_f32 v[34:35], v[28:29], v[58:59]
	v_lshlrev_b32_e32 v56, 16, v21
	v_and_b32_e32 v57, 0xffff0000, v21
	v_cvt_pk_bf16_f32 v20, v34, v35
	v_pk_mul_f32 v[34:35], v[30:31], v[56:57]
	v_and_b32_e32 v65, 0xffff0000, v22
	v_cvt_pk_bf16_f32 v21, v34, v35
	v_pk_mul_f32 v[34:35], v[24:25], v[64:65]
	v_lshlrev_b32_e32 v62, 16, v23
	v_and_b32_e32 v63, 0xffff0000, v23
	v_cvt_pk_bf16_f32 v22, v34, v35
	v_pk_mul_f32 v[34:35], v[26:27], v[62:63]
	s_waitcnt lgkmcnt(0)
	v_lshlrev_b32_e32 v52, 16, v32
	v_cvt_pk_bf16_f32 v23, v34, v35
	v_and_b32_e32 v53, 0xffff0000, v32
	v_lshlrev_b32_e32 v54, 16, v33
	v_mfma_f32_16x16x32_bf16 v[36:39], v[16:19], v[20:23], 0
	ds_read_b64_tr_b16 v[22:23], v232 offset:1120
	v_and_b32_e32 v55, 0xffff0000, v33
	v_pk_mul_f32 v[20:21], v[28:29], v[52:53]
	v_pk_mul_f32 v[32:33], v[30:31], v[54:55]
	v_cvt_pk_bf16_f32 v20, v20, v21
	s_waitcnt lgkmcnt(0)
	v_lshlrev_b32_e32 v60, 16, v22
	v_and_b32_e32 v61, 0xffff0000, v22
	v_cvt_pk_bf16_f32 v21, v32, v33
	v_pk_mul_f32 v[32:33], v[24:25], v[60:61]
	v_lshlrev_b32_e32 v66, 16, v23
	v_and_b32_e32 v67, 0xffff0000, v23
	v_cvt_pk_bf16_f32 v22, v32, v33
	v_pk_mul_f32 v[32:33], v[26:27], v[66:67]
	s_or_b32 s0, s1, s0
	v_cvt_pk_bf16_f32 v23, v32, v33
	ds_read_b64_tr_b16 v[32:33], v232 offset:64
	ds_read_b64_tr_b16 v[34:35], v232 offset:1152
	v_mfma_f32_16x16x32_bf16 v[20:23], v[16:19], v[20:23], 0
	s_waitcnt lgkmcnt(1)
	v_lshlrev_b32_e32 v68, 16, v32
	v_and_b32_e32 v69, 0xffff0000, v32
	v_pk_mul_f32 v[40:41], v[28:29], v[68:69]
	v_lshlrev_b32_e32 v70, 16, v33
	v_and_b32_e32 v71, 0xffff0000, v33
	v_cvt_pk_bf16_f32 v32, v40, v41
	v_pk_mul_f32 v[40:41], v[30:31], v[70:71]
	s_waitcnt lgkmcnt(0)
	v_lshlrev_b32_e32 v72, 16, v34
	v_and_b32_e32 v73, 0xffff0000, v34
	v_cvt_pk_bf16_f32 v33, v40, v41
	v_pk_mul_f32 v[40:41], v[24:25], v[72:73]
	v_lshlrev_b32_e32 v74, 16, v35
	v_and_b32_e32 v75, 0xffff0000, v35
	v_cvt_pk_bf16_f32 v34, v40, v41
	v_pk_mul_f32 v[40:41], v[26:27], v[74:75]
	s_or_b32 s0, s64, s0
	v_cvt_pk_bf16_f32 v35, v40, v41
	ds_read_b64_tr_b16 v[40:41], v232 offset:96
	ds_read_b64_tr_b16 v[42:43], v232 offset:1184
	v_mfma_f32_16x16x32_bf16 v[32:35], v[16:19], v[32:35], 0
	s_waitcnt lgkmcnt(1)
	v_lshlrev_b32_e32 v76, 16, v40
	v_and_b32_e32 v77, 0xffff0000, v40
	v_lshlrev_b32_e32 v78, 16, v41
	v_and_b32_e32 v79, 0xffff0000, v41
	s_waitcnt lgkmcnt(0)
	v_lshlrev_b32_e32 v84, 16, v42
	v_and_b32_e32 v85, 0xffff0000, v42
	v_pk_mul_f32 v[28:29], v[28:29], v[76:77]
	v_pk_mul_f32 v[30:31], v[30:31], v[78:79]
	v_pk_mul_f32 v[24:25], v[24:25], v[84:85]
	v_lshlrev_b32_e32 v90, 16, v43
	v_and_b32_e32 v91, 0xffff0000, v43
	v_cvt_pk_bf16_f32 v28, v28, v29
	v_cvt_pk_bf16_f32 v29, v30, v31
	v_cvt_pk_bf16_f32 v30, v24, v25
	v_pk_mul_f32 v[24:25], v[26:27], v[90:91]
	s_lshl_b32 s0, s0, 1
	v_cvt_pk_bf16_f32 v31, v24, v25
	s_ashr_i32 s1, s0, 31
	s_lshl_b64 s[60:61], s[0:1], 15
	v_mfma_f32_16x16x32_bf16 v[24:27], v[16:19], v[28:31], 0
	ds_read_b128 v[48:51], v231 offset:128
	ds_read_b128 v[44:47], v231 offset:144
	ds_read_b64_tr_b16 v[28:29], v232 offset:8704
	ds_read_b64_tr_b16 v[30:31], v232 offset:9792
	v_mov_b32_e32 v123, v189
	v_mov_b32_e32 v125, v189
	v_mov_b32_e32 v127, v189
	s_waitcnt lgkmcnt(1)
	v_lshlrev_b32_e32 v82, 16, v28
	v_and_b32_e32 v83, 0xffff0000, v28
	v_pk_mul_f32 v[40:41], v[48:49], v[82:83]
	v_lshlrev_b32_e32 v80, 16, v29
	v_and_b32_e32 v81, 0xffff0000, v29
	v_cvt_pk_bf16_f32 v28, v40, v41
	v_pk_mul_f32 v[40:41], v[50:51], v[80:81]
	s_waitcnt lgkmcnt(0)
	v_lshlrev_b32_e32 v88, 16, v30
	v_and_b32_e32 v89, 0xffff0000, v30
	v_cvt_pk_bf16_f32 v29, v40, v41
	v_pk_mul_f32 v[40:41], v[44:45], v[88:89]
	v_lshlrev_b32_e32 v86, 16, v31
	v_and_b32_e32 v87, 0xffff0000, v31
	v_cvt_pk_bf16_f32 v30, v40, v41
	v_pk_mul_f32 v[40:41], v[46:47], v[86:87]
	v_mov_b32_e32 v129, v189
	v_cvt_pk_bf16_f32 v31, v40, v41
	v_mov_b32_e32 v131, v189
	v_mov_b32_e32 v133, v189
	v_mfma_f32_16x16x32_bf16 v[28:31], v[12:15], v[28:31], v[36:39]
	s_nop 2
	ds_read_b64_tr_b16 v[36:37], v232 offset:8736
	ds_read_b64_tr_b16 v[38:39], v232 offset:9824
	v_mov_b32_e32 v135, v189
	v_mov_b32_e32 v137, v189
	v_mov_b32_e32 v139, v189
	s_waitcnt lgkmcnt(1)
	v_lshlrev_b32_e32 v92, 16, v36
	v_and_b32_e32 v93, 0xffff0000, v36
	v_pk_mul_f32 v[40:41], v[48:49], v[92:93]
	v_lshlrev_b32_e32 v94, 16, v37
	v_and_b32_e32 v95, 0xffff0000, v37
	v_cvt_pk_bf16_f32 v36, v40, v41
	v_pk_mul_f32 v[40:41], v[50:51], v[94:95]
	s_waitcnt lgkmcnt(0)
	v_lshlrev_b32_e32 v96, 16, v38
	v_and_b32_e32 v97, 0xffff0000, v38
	v_cvt_pk_bf16_f32 v37, v40, v41
	v_pk_mul_f32 v[40:41], v[44:45], v[96:97]
	v_lshlrev_b32_e32 v98, 16, v39
	v_and_b32_e32 v99, 0xffff0000, v39
	v_cvt_pk_bf16_f32 v38, v40, v41
	v_pk_mul_f32 v[40:41], v[46:47], v[98:99]
	v_mov_b32_e32 v141, v189
	v_cvt_pk_bf16_f32 v39, v40, v41
	v_mov_b32_e32 v143, v189
	v_mov_b32_e32 v145, v189
	v_mfma_f32_16x16x32_bf16 v[40:43], v[12:15], v[36:39], v[20:23]
	s_nop 2
	ds_read_b64_tr_b16 v[20:21], v232 offset:8768
	ds_read_b64_tr_b16 v[22:23], v232 offset:9856
	v_mov_b32_e32 v147, v189
	s_add_i32 s31, s31, s88
	s_waitcnt lgkmcnt(1)
; #define LAS __attribute__((address_space(3)))
; #define MFMA16(a, b, c) __builtin_amdgcn_mfma_f32_16x16x32_bf16((a), (b), (c), 0, 0, 0)
; DI unsigned pk2(float lo, float hi) { f32x2_t v = {lo, hi}; bf16x2_t b = __builtin_convertvector(v, bf16x2_t); return __builtin_bit_cast(unsigned, b); }
; DI s16x4 vtr(const LAS char* p) { return __builtin_bit_cast(s16x4, __builtin_amdgcn_ds_read_tr16_b64_v4i16((LAS s16x4*)p)); }
; DI void ssd_part1_unit(int u, const bf16* PROJ, float* DT, const bf16* H, const bf16* wdtb_l, const float* dt_bias_l, const float* cw, const float* cb, const float* a_log_l, float* STATES, float* TOT,
;                        LAS unsigned char* ldsu, int tid, int wave, int lane) {
;     ...
; #pragma unroll
;         for (int ks = 0; ks < 4; ++ks) {
;             const f32x4 w0 = *(const LAS f32x4*)(wtab + combo * 128 + 32 * ks + 8 * g), w1 = *(const LAS f32x4*)(wtab + combo * 128 + 32 * ks + 8 * g + 4);
; #pragma unroll
;             for (int pt = 0; pt < 4; ++pt) {
;                 const LAS char* xp = XS + (32 * ks + 8 * g + q) * IMG_PITCH + (hh * 64 + 16 * pt) * 2 + 8 * p;
;                 const u32x2 lo = __builtin_bit_cast(u32x2, vtr(xp)), hi = __builtin_bit_cast(u32x2, vtr(xp + 4 * IMG_PITCH));
;                 u32x4 af; af.x = pk2(bflo(lo.x) * w0[0], bfhi(lo.x) * w0[1]); af.y = pk2(bflo(lo.y) * w0[2], bfhi(lo.y) * w0[3]);
;                 af.z = pk2(bflo(hi.x) * w1[0], bfhi(hi.x) * w1[1]); af.w = pk2(bflo(hi.y) * w1[2], bfhi(hi.y) * w1[3]);
;                 acc[pt] = MFMA16(__builtin_bit_cast(bf16x8, af), bfr[ks], acc[pt]);
;             }
;         }
	v_lshlrev_b32_e32 v148, 16, v20
	v_and_b32_e32 v149, 0xffff0000, v20
	v_pk_mul_f32 v[36:37], v[48:49], v[148:149]
	v_lshlrev_b32_e32 v150, 16, v21
	v_and_b32_e32 v151, 0xffff0000, v21
	v_cvt_pk_bf16_f32 v20, v36, v37
	v_pk_mul_f32 v[36:37], v[50:51], v[150:151]
	s_waitcnt lgkmcnt(0)
	v_lshlrev_b32_e32 v152, 16, v22
	v_and_b32_e32 v153, 0xffff0000, v22
	v_cvt_pk_bf16_f32 v21, v36, v37
	v_pk_mul_f32 v[36:37], v[44:45], v[152:153]
	v_lshlrev_b32_e32 v154, 16, v23
	v_and_b32_e32 v155, 0xffff0000, v23
	v_cvt_pk_bf16_f32 v22, v36, v37
	v_pk_mul_f32 v[36:37], v[46:47], v[154:155]
	s_nop 0
	v_cvt_pk_bf16_f32 v23, v36, v37
	s_nop 1
	v_mfma_f32_16x16x32_bf16 v[32:35], v[12:15], v[20:23], v[32:35]
	ds_read_b64_tr_b16 v[20:21], v232 offset:8800
	ds_read_b64_tr_b16 v[22:23], v232 offset:9888
	s_waitcnt lgkmcnt(1)
	v_lshlrev_b32_e32 v156, 16, v20
	v_and_b32_e32 v157, 0xffff0000, v20
	v_pk_mul_f32 v[36:37], v[48:49], v[156:157]
	v_lshlrev_b32_e32 v48, 16, v21
	v_and_b32_e32 v49, 0xffff0000, v21
	v_cvt_pk_bf16_f32 v20, v36, v37
	v_pk_mul_f32 v[36:37], v[50:51], v[48:49]
	s_waitcnt lgkmcnt(0)
	v_lshlrev_b32_e32 v160, 16, v22
	v_and_b32_e32 v161, 0xffff0000, v22
	v_cvt_pk_bf16_f32 v21, v36, v37
	v_pk_mul_f32 v[36:37], v[44:45], v[160:161]
	v_lshlrev_b32_e32 v166, 16, v23
	v_and_b32_e32 v167, 0xffff0000, v23
	v_cvt_pk_bf16_f32 v22, v36, v37
	v_pk_mul_f32 v[36:37], v[46:47], v[166:167]
	s_nop 0
	v_cvt_pk_bf16_f32 v23, v36, v37
	s_nop 1
	v_mfma_f32_16x16x32_bf16 v[20:23], v[12:15], v[20:23], v[24:27]
	ds_read_b128 v[44:47], v231 offset:256
	ds_read_b128 v[36:39], v231 offset:272
	s_nop 0
	ds_read_b64_tr_b16 v[24:25], v232 offset:17408
	ds_read_b64_tr_b16 v[26:27], v232 offset:18496
	s_waitcnt lgkmcnt(1)
	v_lshlrev_b32_e32 v158, 16, v24
	v_and_b32_e32 v159, 0xffff0000, v24
	v_pk_mul_f32 v[50:51], v[44:45], v[158:159]
	s_waitcnt lgkmcnt(0)
	v_lshlrev_b32_e32 v164, 16, v26
	v_cvt_pk_bf16_f32 v24, v50, v51
	v_lshlrev_b32_e32 v50, 16, v25
	v_and_b32_e32 v51, 0xffff0000, v25
	v_pk_mul_f32 v[162:163], v[46:47], v[50:51]
	v_and_b32_e32 v165, 0xffff0000, v26
	v_cvt_pk_bf16_f32 v25, v162, v163
	v_pk_mul_f32 v[162:163], v[36:37], v[164:165]
	s_nop 0
	v_cvt_pk_bf16_f32 v26, v162, v163
	v_lshlrev_b32_e32 v162, 16, v27
	v_and_b32_e32 v163, 0xffff0000, v27
	v_pk_mul_f32 v[168:169], v[38:39], v[162:163]
	s_nop 0
	v_cvt_pk_bf16_f32 v27, v168, v169
	s_nop 1
	v_mfma_f32_16x16x32_bf16 v[24:27], v[8:11], v[24:27], v[28:31]
	s_nop 2
	ds_read_b64_tr_b16 v[28:29], v232 offset:17440
	ds_read_b64_tr_b16 v[30:31], v232 offset:18528
	s_waitcnt lgkmcnt(1)
	v_lshlrev_b32_e32 v168, 16, v28
	v_and_b32_e32 v169, 0xffff0000, v28
	v_pk_mul_f32 v[170:171], v[44:45], v[168:169]
	s_nop 0
	v_cvt_pk_bf16_f32 v28, v170, v171
	v_lshlrev_b32_e32 v170, 16, v29
	v_and_b32_e32 v171, 0xffff0000, v29
	v_pk_mul_f32 v[172:173], v[46:47], v[170:171]
	s_nop 0
	v_cvt_pk_bf16_f32 v29, v172, v173
	s_waitcnt lgkmcnt(0)
	v_lshlrev_b32_e32 v172, 16, v30
	v_and_b32_e32 v173, 0xffff0000, v30
	v_pk_mul_f32 v[174:175], v[36:37], v[172:173]
	s_nop 0
	v_cvt_pk_bf16_f32 v30, v174, v175
	v_lshlrev_b32_e32 v174, 16, v31
	v_and_b32_e32 v175, 0xffff0000, v31
	v_pk_mul_f32 v[176:177], v[38:39], v[174:175]
	s_nop 0
	v_cvt_pk_bf16_f32 v31, v176, v177
	s_nop 1
	v_mfma_f32_16x16x32_bf16 v[28:31], v[8:11], v[28:31], v[40:43]
	s_nop 2
	ds_read_b64_tr_b16 v[40:41], v232 offset:17472
	ds_read_b64_tr_b16 v[42:43], v232 offset:18560
	s_waitcnt lgkmcnt(1)
	v_lshlrev_b32_e32 v176, 16, v40
	v_and_b32_e32 v177, 0xffff0000, v40
	v_pk_mul_f32 v[178:179], v[44:45], v[176:177]
	s_nop 0
	v_cvt_pk_bf16_f32 v40, v178, v179
	v_lshlrev_b32_e32 v178, 16, v41
	v_and_b32_e32 v179, 0xffff0000, v41
	v_pk_mul_f32 v[180:181], v[46:47], v[178:179]
	s_nop 0
	v_cvt_pk_bf16_f32 v41, v180, v181
	s_waitcnt lgkmcnt(0)
	v_lshlrev_b32_e32 v180, 16, v42
	v_and_b32_e32 v181, 0xffff0000, v42
	v_pk_mul_f32 v[182:183], v[36:37], v[180:181]
	s_nop 0
	v_cvt_pk_bf16_f32 v42, v182, v183
	v_lshlrev_b32_e32 v182, 16, v43
	v_and_b32_e32 v183, 0xffff0000, v43
	v_pk_mul_f32 v[184:185], v[38:39], v[182:183]
	s_nop 0
	v_cvt_pk_bf16_f32 v43, v184, v185
	s_nop 1
	v_mfma_f32_16x16x32_bf16 v[32:35], v[8:11], v[40:43], v[32:35]
	ds_read_b64_tr_b16 v[40:41], v232 offset:17504
	ds_read_b64_tr_b16 v[42:43], v232 offset:18592
	s_waitcnt lgkmcnt(1)
	v_lshlrev_b32_e32 v184, 16, v40
	v_and_b32_e32 v185, 0xffff0000, v40
	v_pk_mul_f32 v[44:45], v[44:45], v[184:185]
	s_waitcnt lgkmcnt(0)
	v_lshlrev_b32_e32 v198, 16, v42
	v_and_b32_e32 v199, 0xffff0000, v42
	v_cvt_pk_bf16_f32 v40, v44, v45
	v_lshlrev_b32_e32 v44, 16, v41
	v_and_b32_e32 v45, 0xffff0000, v41
	v_pk_mul_f32 v[36:37], v[36:37], v[198:199]
	v_lshlrev_b32_e32 v204, 16, v43
	v_and_b32_e32 v205, 0xffff0000, v43
	v_pk_mul_f32 v[46:47], v[46:47], v[44:45]
	v_cvt_pk_bf16_f32 v42, v36, v37
	v_pk_mul_f32 v[36:37], v[38:39], v[204:205]
	v_cvt_pk_bf16_f32 v41, v46, v47
	v_cvt_pk_bf16_f32 v43, v36, v37
	s_nop 1
	v_mfma_f32_16x16x32_bf16 v[20:23], v[8:11], v[40:43], v[20:23]
	ds_read_b128 v[40:43], v231 offset:384
	ds_read_b128 v[36:39], v231 offset:400
	ds_read_b64_tr_b16 v[46:47], v232 offset:26112
	ds_read_b64_tr_b16 v[200:201], v232 offset:27200
	s_waitcnt lgkmcnt(1)
	v_lshlrev_b32_e32 v186, 16, v46
	v_and_b32_e32 v187, 0xffff0000, v46
	v_pk_mul_f32 v[202:203], v[40:41], v[186:187]
	v_lshlrev_b32_e32 v46, 16, v47
	v_and_b32_e32 v47, 0xffff0000, v47
	v_cvt_pk_bf16_f32 v206, v202, v203
	v_pk_mul_f32 v[202:203], v[42:43], v[46:47]
	s_nop 0
	v_cvt_pk_bf16_f32 v207, v202, v203
	s_waitcnt lgkmcnt(0)
; #define MFMA16(a, b, c) __builtin_amdgcn_mfma_f32_16x16x32_bf16((a), (b), (c), 0, 0, 0)
; DI unsigned pk2(float lo, float hi) { f32x2_t v = {lo, hi}; bf16x2_t b = __builtin_convertvector(v, bf16x2_t); return __builtin_bit_cast(unsigned, b); }
; DI void ssd_part1_unit(int u, const bf16* PROJ, float* DT, const bf16* H, const bf16* wdtb_l, const float* dt_bias_l, const float* cw, const float* cb, const float* a_log_l, float* STATES, float* TOT,
;                        LAS unsigned char* ldsu, int tid, int wave, int lane) {
;     ...
;                 u32x4 af; af.x = pk2(bflo(lo.x) * w0[0], bfhi(lo.x) * w0[1]); af.y = pk2(bflo(lo.y) * w0[2], bfhi(lo.y) * w0[3]);
;                 af.z = pk2(bflo(hi.x) * w1[0], bfhi(hi.x) * w1[1]); af.w = pk2(bflo(hi.y) * w1[2], bfhi(hi.y) * w1[3]);
;                 acc[pt] = MFMA16(__builtin_bit_cast(bf16x8, af), bfr[ks], acc[pt]);
;             }
;         }
;         float* sb = STATES + ((size_t)(((b * 16 + c) * 4 + h) * 2 + dir) * 64) * 128;
; #pragma unroll
;         for (int pt = 0; pt < 4; ++pt)
; #pragma unroll
;             for (int i = 0; i < 4; ++i) sb[(size_t)(16 * pt + 4 * g + i) * 128 + 16 * wave + r] = acc[pt][i];
	v_lshlrev_b32_e32 v202, 16, v200
	v_and_b32_e32 v203, 0xffff0000, v200
	v_lshlrev_b32_e32 v200, 16, v201
	v_and_b32_e32 v201, 0xffff0000, v201
	v_pk_mul_f32 v[208:209], v[36:37], v[202:203]
	v_pk_mul_f32 v[210:211], v[38:39], v[200:201]
	v_cvt_pk_bf16_f32 v208, v208, v209
	v_cvt_pk_bf16_f32 v209, v210, v211
	s_nop 1
	v_mfma_f32_16x16x32_bf16 v[24:27], v[4:7], v[206:209], v[24:27]
	ds_read_b64_tr_b16 v[208:209], v232 offset:26144
	ds_read_b64_tr_b16 v[212:213], v232 offset:27232
	s_waitcnt lgkmcnt(1)
	v_lshlrev_b32_e32 v206, 16, v208
	v_and_b32_e32 v207, 0xffff0000, v208
	v_pk_mul_f32 v[210:211], v[40:41], v[206:207]
	v_lshlrev_b32_e32 v208, 16, v209
	v_and_b32_e32 v209, 0xffff0000, v209
	v_cvt_pk_bf16_f32 v214, v210, v211
	v_pk_mul_f32 v[210:211], v[42:43], v[208:209]
	s_nop 0
	v_cvt_pk_bf16_f32 v215, v210, v211
	s_waitcnt lgkmcnt(0)
	v_lshlrev_b32_e32 v210, 16, v212
	v_and_b32_e32 v211, 0xffff0000, v212
	v_lshlrev_b32_e32 v212, 16, v213
	v_and_b32_e32 v213, 0xffff0000, v213
	v_pk_mul_f32 v[216:217], v[36:37], v[210:211]
	v_pk_mul_f32 v[218:219], v[38:39], v[212:213]
	v_cvt_pk_bf16_f32 v216, v216, v217
	v_cvt_pk_bf16_f32 v217, v218, v219
	s_nop 1
	v_mfma_f32_16x16x32_bf16 v[28:31], v[4:7], v[214:217], v[28:31]
	ds_read_b64_tr_b16 v[216:217], v232 offset:26176
	ds_read_b64_tr_b16 v[220:221], v232 offset:27264
	s_waitcnt lgkmcnt(1)
	v_lshlrev_b32_e32 v214, 16, v216
	v_and_b32_e32 v215, 0xffff0000, v216
	v_pk_mul_f32 v[218:219], v[40:41], v[214:215]
	v_lshlrev_b32_e32 v216, 16, v217
	v_and_b32_e32 v217, 0xffff0000, v217
	v_cvt_pk_bf16_f32 v248, v218, v219
	v_pk_mul_f32 v[218:219], v[42:43], v[216:217]
	s_nop 0
	v_cvt_pk_bf16_f32 v249, v218, v219
	s_waitcnt lgkmcnt(0)
	v_lshlrev_b32_e32 v218, 16, v220
	v_and_b32_e32 v219, 0xffff0000, v220
	v_pk_mul_f32 v[222:223], v[36:37], v[218:219]
	v_lshlrev_b32_e32 v220, 16, v221
	v_and_b32_e32 v221, 0xffff0000, v221
	v_cvt_pk_bf16_f32 v250, v222, v223
	v_pk_mul_f32 v[222:223], v[38:39], v[220:221]
	s_nop 0
	v_cvt_pk_bf16_f32 v251, v222, v223
	s_nop 1
	v_mfma_f32_16x16x32_bf16 v[32:35], v[4:7], v[248:251], v[32:35]
	ds_read_b64_tr_b16 v[248:249], v232 offset:26208
	ds_read_b64_tr_b16 v[250:251], v232 offset:27296
	s_waitcnt lgkmcnt(1)
	v_lshlrev_b32_e32 v222, 16, v248
	v_and_b32_e32 v223, 0xffff0000, v248
	v_pk_mul_f32 v[40:41], v[40:41], v[222:223]
	s_nop 0
	v_cvt_pk_bf16_f32 v248, v40, v41
	v_lshlrev_b32_e32 v40, 16, v249
	v_and_b32_e32 v41, 0xffff0000, v249
	v_pk_mul_f32 v[42:43], v[42:43], v[40:41]
	s_nop 0
	v_cvt_pk_bf16_f32 v249, v42, v43
	s_waitcnt lgkmcnt(0)
	v_lshlrev_b32_e32 v42, 16, v250
	v_and_b32_e32 v43, 0xffff0000, v250
	v_pk_mul_f32 v[36:37], v[36:37], v[42:43]
	s_nop 0
	v_cvt_pk_bf16_f32 v250, v36, v37
	v_lshlrev_b32_e32 v36, 16, v251
	v_and_b32_e32 v37, 0xffff0000, v251
	v_pk_mul_f32 v[38:39], v[38:39], v[36:37]
	s_nop 0
	v_cvt_pk_bf16_f32 v251, v38, v39
	v_lshl_add_u64 v[38:39], v[112:113], 0, s[60:61]
	s_or_b32 s60, s0, 1
	v_mfma_f32_16x16x32_bf16 v[20:23], v[4:7], v[248:251], v[20:23]
	s_nop 7
	v_lshl_add_u64 v[248:249], v[38:39], 0, v[124:125]
	global_store_dwordx4 v[248:249], v[24:27], off
	v_lshl_add_u64 v[248:249], v[38:39], 0, v[126:127]
	global_store_dwordx4 v[248:249], v[28:31], off
	v_lshl_add_u64 v[248:249], v[38:39], 0, v[128:129]
	global_store_dwordx4 v[248:249], v[32:35], off
	v_lshl_add_u64 v[248:249], v[38:39], 0, v[130:131]
	global_store_dwordx4 v[248:249], v[20:23], off
	s_nop 1
	ds_read_b128 v[20:23], v231 offset:512
	ds_read_b128 v[24:27], v231 offset:528
	s_ashr_i32 s61, s60, 31
	s_lshl_b64 s[60:61], s[60:61], 15
	s_waitcnt lgkmcnt(1)
	v_pk_mul_f32 v[28:29], v[20:21], v[58:59]
	v_pk_mul_f32 v[30:31], v[22:23], v[56:57]
	v_cvt_pk_bf16_f32 v28, v28, v29
	v_cvt_pk_bf16_f32 v29, v30, v31
	s_waitcnt lgkmcnt(0)
	v_pk_mul_f32 v[30:31], v[24:25], v[64:65]
	v_pk_mul_f32 v[32:33], v[26:27], v[62:63]
	v_cvt_pk_bf16_f32 v30, v30, v31
	v_cvt_pk_bf16_f32 v31, v32, v33
	v_pk_mul_f32 v[32:33], v[20:21], v[52:53]
	v_pk_mul_f32 v[34:35], v[22:23], v[54:55]
	v_cvt_pk_bf16_f32 v32, v32, v33
	v_cvt_pk_bf16_f32 v33, v34, v35
	v_pk_mul_f32 v[34:35], v[24:25], v[60:61]
	v_pk_mul_f32 v[38:39], v[26:27], v[66:67]
	v_cvt_pk_bf16_f32 v34, v34, v35
	v_cvt_pk_bf16_f32 v35, v38, v39
	v_pk_mul_f32 v[38:39], v[20:21], v[68:69]
	v_pk_mul_f32 v[20:21], v[20:21], v[76:77]
	v_cvt_pk_bf16_f32 v52, v38, v39
	v_pk_mul_f32 v[38:39], v[22:23], v[70:71]
	v_pk_mul_f32 v[22:23], v[22:23], v[78:79]
	v_cvt_pk_bf16_f32 v53, v38, v39
	v_pk_mul_f32 v[38:39], v[24:25], v[72:73]
	v_cvt_pk_bf16_f32 v20, v20, v21
	v_cvt_pk_bf16_f32 v21, v22, v23
	v_pk_mul_f32 v[22:23], v[24:25], v[84:85]
	v_pk_mul_f32 v[24:25], v[26:27], v[90:91]
	v_cvt_pk_bf16_f32 v54, v38, v39
	v_pk_mul_f32 v[38:39], v[26:27], v[74:75]
	v_cvt_pk_bf16_f32 v22, v22, v23
	v_cvt_pk_bf16_f32 v23, v24, v25
	ds_read_b128 v[24:27], v231 offset:640
	ds_read_b128 v[56:59], v231 offset:656
	v_cvt_pk_bf16_f32 v55, v38, v39
	v_mfma_f32_16x16x32_bf16 v[28:31], v[16:19], v[28:31], 0
	s_waitcnt lgkmcnt(1)
	v_pk_mul_f32 v[38:39], v[24:25], v[82:83]
	s_nop 0
	v_cvt_pk_bf16_f32 v60, v38, v39
	v_pk_mul_f32 v[38:39], v[26:27], v[80:81]
	v_mfma_f32_16x16x32_bf16 v[32:35], v[16:19], v[32:35], 0
	v_cvt_pk_bf16_f32 v61, v38, v39
	s_waitcnt lgkmcnt(0)
; #define LAS __attribute__((address_space(3)))
; #define MFMA16(a, b, c) __builtin_amdgcn_mfma_f32_16x16x32_bf16((a), (b), (c), 0, 0, 0)
; DI unsigned pk2(float lo, float hi) { f32x2_t v = {lo, hi}; bf16x2_t b = __builtin_convertvector(v, bf16x2_t); return __builtin_bit_cast(unsigned, b); }
; DI s16x4 vtr(const LAS char* p) { return __builtin_bit_cast(s16x4, __builtin_amdgcn_ds_read_tr16_b64_v4i16((LAS s16x4*)p)); }
; DI void ssd_part1_unit(int u, const bf16* PROJ, float* DT, const bf16* H, const bf16* wdtb_l, const float* dt_bias_l, const float* cw, const float* cb, const float* a_log_l, float* STATES, float* TOT,
;                        LAS unsigned char* ldsu, int tid, int wave, int lane) {
;     ...
;         for (int ks = 0; ks < 4; ++ks) {
;             const f32x4 w0 = *(const LAS f32x4*)(wtab + combo * 128 + 32 * ks + 8 * g), w1 = *(const LAS f32x4*)(wtab + combo * 128 + 32 * ks + 8 * g + 4);
; #pragma unroll
;             for (int pt = 0; pt < 4; ++pt) {
;                 const LAS char* xp = XS + (32 * ks + 8 * g + q) * IMG_PITCH + (hh * 64 + 16 * pt) * 2 + 8 * p;
;                 const u32x2 lo = __builtin_bit_cast(u32x2, vtr(xp)), hi = __builtin_bit_cast(u32x2, vtr(xp + 4 * IMG_PITCH));
;                 u32x4 af; af.x = pk2(bflo(lo.x) * w0[0], bfhi(lo.x) * w0[1]); af.y = pk2(bflo(lo.y) * w0[2], bfhi(lo.y) * w0[3]);
;                 af.z = pk2(bflo(hi.x) * w1[0], bfhi(hi.x) * w1[1]); af.w = pk2(bflo(hi.y) * w1[2], bfhi(hi.y) * w1[3]);
;                 acc[pt] = MFMA16(__builtin_bit_cast(bf16x8, af), bfr[ks], acc[pt]);
;             }
;         }
;         float* sb = STATES + ((size_t)(((b * 16 + c) * 4 + h) * 2 + dir) * 64) * 128;
; #pragma unroll
;         for (int pt = 0; pt < 4; ++pt)
; #pragma unroll
;             for (int i = 0; i < 4; ++i) sb[(size_t)(16 * pt + 4 * g + i) * 128 + 16 * wave + r] = acc[pt][i];
	v_pk_mul_f32 v[38:39], v[56:57], v[88:89]
	s_nop 0
	v_cvt_pk_bf16_f32 v62, v38, v39
	v_pk_mul_f32 v[38:39], v[58:59], v[86:87]
	v_mfma_f32_16x16x32_bf16 v[20:23], v[16:19], v[20:23], 0
	v_cvt_pk_bf16_f32 v63, v38, v39
	v_pk_mul_f32 v[38:39], v[24:25], v[92:93]
	s_nop 0
	v_mfma_f32_16x16x32_bf16 v[28:31], v[12:15], v[60:63], v[28:31]
	v_cvt_pk_bf16_f32 v60, v38, v39
	v_pk_mul_f32 v[38:39], v[26:27], v[94:95]
	s_nop 0
	v_cvt_pk_bf16_f32 v61, v38, v39
	v_pk_mul_f32 v[38:39], v[56:57], v[96:97]
	v_mfma_f32_16x16x32_bf16 v[52:55], v[16:19], v[52:55], 0
	v_cvt_pk_bf16_f32 v62, v38, v39
	v_pk_mul_f32 v[38:39], v[58:59], v[98:99]
	s_nop 0
	v_cvt_pk_bf16_f32 v63, v38, v39
	v_pk_mul_f32 v[38:39], v[24:25], v[148:149]
	v_pk_mul_f32 v[24:25], v[24:25], v[156:157]
	v_mfma_f32_16x16x32_bf16 v[32:35], v[12:15], v[60:63], v[32:35]
	v_cvt_pk_bf16_f32 v60, v38, v39
	v_pk_mul_f32 v[38:39], v[26:27], v[150:151]
	v_pk_mul_f32 v[26:27], v[26:27], v[48:49]
	v_cvt_pk_bf16_f32 v61, v38, v39
	v_pk_mul_f32 v[38:39], v[56:57], v[152:153]
	v_cvt_pk_bf16_f32 v24, v24, v25
	v_cvt_pk_bf16_f32 v62, v38, v39
	v_pk_mul_f32 v[38:39], v[58:59], v[154:155]
	v_cvt_pk_bf16_f32 v25, v26, v27
	v_cvt_pk_bf16_f32 v63, v38, v39
	v_pk_mul_f32 v[26:27], v[56:57], v[160:161]
	v_pk_mul_f32 v[38:39], v[58:59], v[166:167]
	v_cvt_pk_bf16_f32 v26, v26, v27
	v_cvt_pk_bf16_f32 v27, v38, v39
	v_mfma_f32_16x16x32_bf16 v[52:55], v[12:15], v[60:63], v[52:55]
	s_nop 0
	v_mfma_f32_16x16x32_bf16 v[20:23], v[12:15], v[24:27], v[20:23]
	ds_read_b128 v[24:27], v231 offset:768
	ds_read_b128 v[56:59], v231 offset:784
	s_waitcnt lgkmcnt(1)
	v_pk_mul_f32 v[38:39], v[24:25], v[158:159]
	s_nop 0
	v_cvt_pk_bf16_f32 v48, v38, v39
	v_pk_mul_f32 v[38:39], v[26:27], v[50:51]
	s_nop 0
	v_cvt_pk_bf16_f32 v49, v38, v39
	s_waitcnt lgkmcnt(0)
	v_pk_mul_f32 v[38:39], v[56:57], v[164:165]
	s_nop 0
	v_cvt_pk_bf16_f32 v50, v38, v39
	v_pk_mul_f32 v[38:39], v[58:59], v[162:163]
	s_nop 0
	v_cvt_pk_bf16_f32 v51, v38, v39
	v_pk_mul_f32 v[38:39], v[24:25], v[168:169]
	s_nop 0
	v_mfma_f32_16x16x32_bf16 v[28:31], v[8:11], v[48:51], v[28:31]
	v_cvt_pk_bf16_f32 v48, v38, v39
	v_pk_mul_f32 v[38:39], v[26:27], v[170:171]
	s_nop 0
	v_cvt_pk_bf16_f32 v49, v38, v39
	v_pk_mul_f32 v[38:39], v[56:57], v[172:173]
	s_nop 0
	v_cvt_pk_bf16_f32 v50, v38, v39
	v_pk_mul_f32 v[38:39], v[58:59], v[174:175]
	s_nop 0
	v_cvt_pk_bf16_f32 v51, v38, v39
	v_pk_mul_f32 v[38:39], v[24:25], v[176:177]
	v_pk_mul_f32 v[24:25], v[24:25], v[184:185]
	v_mfma_f32_16x16x32_bf16 v[32:35], v[8:11], v[48:51], v[32:35]
	v_cvt_pk_bf16_f32 v48, v38, v39
	v_pk_mul_f32 v[38:39], v[26:27], v[178:179]
	v_pk_mul_f32 v[26:27], v[26:27], v[44:45]
	v_cvt_pk_bf16_f32 v49, v38, v39
	v_pk_mul_f32 v[38:39], v[56:57], v[180:181]
	v_cvt_pk_bf16_f32 v24, v24, v25
	v_cvt_pk_bf16_f32 v50, v38, v39
	v_pk_mul_f32 v[38:39], v[58:59], v[182:183]
	v_cvt_pk_bf16_f32 v25, v26, v27
	v_cvt_pk_bf16_f32 v51, v38, v39
	v_pk_mul_f32 v[26:27], v[56:57], v[198:199]
	v_pk_mul_f32 v[38:39], v[58:59], v[204:205]
	v_cvt_pk_bf16_f32 v26, v26, v27
	v_cvt_pk_bf16_f32 v27, v38, v39
	v_mfma_f32_16x16x32_bf16 v[48:51], v[8:11], v[48:51], v[52:55]
	s_nop 0
	v_mfma_f32_16x16x32_bf16 v[20:23], v[8:11], v[24:27], v[20:23]
	ds_read_b128 v[24:27], v231 offset:896
	ds_read_b128 v[52:55], v231 offset:912
	s_waitcnt lgkmcnt(1)
	v_pk_mul_f32 v[38:39], v[24:25], v[186:187]
	s_nop 0
	v_cvt_pk_bf16_f32 v44, v38, v39
	v_pk_mul_f32 v[38:39], v[26:27], v[46:47]
	s_waitcnt lgkmcnt(0)
	v_pk_mul_f32 v[36:37], v[54:55], v[36:37]
	v_cvt_pk_bf16_f32 v45, v38, v39
	v_pk_mul_f32 v[38:39], v[52:53], v[202:203]
	s_nop 0
	v_cvt_pk_bf16_f32 v46, v38, v39
	v_pk_mul_f32 v[38:39], v[54:55], v[200:201]
	s_nop 0
	v_cvt_pk_bf16_f32 v47, v38, v39
	v_pk_mul_f32 v[38:39], v[24:25], v[206:207]
	s_nop 0
	v_mfma_f32_16x16x32_bf16 v[28:31], v[4:7], v[44:47], v[28:31]
	v_cvt_pk_bf16_f32 v44, v38, v39
	v_pk_mul_f32 v[38:39], v[26:27], v[208:209]
	s_nop 0
	v_cvt_pk_bf16_f32 v45, v38, v39
	v_pk_mul_f32 v[38:39], v[52:53], v[210:211]
	s_nop 0
	v_cvt_pk_bf16_f32 v46, v38, v39
	v_pk_mul_f32 v[38:39], v[54:55], v[212:213]
	s_nop 0
	v_cvt_pk_bf16_f32 v47, v38, v39
	v_pk_mul_f32 v[38:39], v[24:25], v[214:215]
	v_pk_mul_f32 v[24:25], v[24:25], v[222:223]
	v_mfma_f32_16x16x32_bf16 v[32:35], v[4:7], v[44:47], v[32:35]
	v_cvt_pk_bf16_f32 v44, v38, v39
	v_pk_mul_f32 v[38:39], v[26:27], v[216:217]
	v_pk_mul_f32 v[26:27], v[26:27], v[40:41]
	v_cvt_pk_bf16_f32 v24, v24, v25
	v_cvt_pk_bf16_f32 v25, v26, v27
	v_pk_mul_f32 v[26:27], v[52:53], v[42:43]
	v_cvt_pk_bf16_f32 v45, v38, v39
	v_cvt_pk_bf16_f32 v26, v26, v27
	v_cvt_pk_bf16_f32 v27, v36, v37
	v_pk_mul_f32 v[38:39], v[52:53], v[218:219]
	s_nop 0
	v_cvt_pk_bf16_f32 v46, v38, v39
	v_pk_mul_f32 v[38:39], v[54:55], v[220:221]
	v_mfma_f32_16x16x32_bf16 v[20:23], v[4:7], v[24:27], v[20:23]
	v_cvt_pk_bf16_f32 v47, v38, v39
	v_lshl_add_u64 v[24:25], v[112:113], 0, s[60:61]
	v_mfma_f32_16x16x32_bf16 v[44:47], v[4:7], v[44:47], v[48:51]
	s_nop 7
	v_lshl_add_u64 v[26:27], v[24:25], 0, v[124:125]
	global_store_dwordx4 v[26:27], v[28:31], off
	v_lshl_add_u64 v[26:27], v[24:25], 0, v[126:127]
	global_store_dwordx4 v[26:27], v[32:35], off
	v_lshl_add_u64 v[26:27], v[24:25], 0, v[128:129]
	global_store_dwordx4 v[26:27], v[44:47], off
	v_lshl_add_u64 v[26:27], v[24:25], 0, v[130:131]
	global_store_dwordx4 v[26:27], v[20:23], off
	s_nop 1
	ds_read_b128 v[28:31], v231 offset:1024
	ds_read_b128 v[24:27], v231 offset:1040
	ds_read_b64_tr_b16 v[22:23], v232 offset:1216
	ds_read_b64_tr_b16 v[20:21], v232 offset:128
	ds_read_b64_tr_b16 v[32:33], v232 offset:160
	s_or_b32 s60, s0, 2
	s_ashr_i32 s61, s60, 31
	s_waitcnt lgkmcnt(2)
; #define LAS __attribute__((address_space(3)))
; #define MFMA16(a, b, c) __builtin_amdgcn_mfma_f32_16x16x32_bf16((a), (b), (c), 0, 0, 0)
; DI unsigned pk2(float lo, float hi) { f32x2_t v = {lo, hi}; bf16x2_t b = __builtin_convertvector(v, bf16x2_t); return __builtin_bit_cast(unsigned, b); }
; DI s16x4 vtr(const LAS char* p) { return __builtin_bit_cast(s16x4, __builtin_amdgcn_ds_read_tr16_b64_v4i16((LAS s16x4*)p)); }
; DI void ssd_part1_unit(int u, const bf16* PROJ, float* DT, const bf16* H, const bf16* wdtb_l, const float* dt_bias_l, const float* cw, const float* cb, const float* a_log_l, float* STATES, float* TOT,
;                        LAS unsigned char* ldsu, int tid, int wave, int lane) {
;     ...
; #pragma unroll
;         for (int ks = 0; ks < 4; ++ks) {
;             const f32x4 w0 = *(const LAS f32x4*)(wtab + combo * 128 + 32 * ks + 8 * g), w1 = *(const LAS f32x4*)(wtab + combo * 128 + 32 * ks + 8 * g + 4);
; #pragma unroll
;             for (int pt = 0; pt < 4; ++pt) {
;                 const LAS char* xp = XS + (32 * ks + 8 * g + q) * IMG_PITCH + (hh * 64 + 16 * pt) * 2 + 8 * p;
;                 const u32x2 lo = __builtin_bit_cast(u32x2, vtr(xp)), hi = __builtin_bit_cast(u32x2, vtr(xp + 4 * IMG_PITCH));
;                 u32x4 af; af.x = pk2(bflo(lo.x) * w0[0], bfhi(lo.x) * w0[1]); af.y = pk2(bflo(lo.y) * w0[2], bfhi(lo.y) * w0[3]);
;                 af.z = pk2(bflo(hi.x) * w1[0], bfhi(hi.x) * w1[1]); af.w = pk2(bflo(hi.y) * w1[2], bfhi(hi.y) * w1[3]);
;                 acc[pt] = MFMA16(__builtin_bit_cast(bf16x8, af), bfr[ks], acc[pt]);
;             }
;         }
	v_lshlrev_b32_e32 v60, 16, v22
	s_waitcnt lgkmcnt(1)
	v_lshlrev_b32_e32 v54, 16, v20
	v_and_b32_e32 v55, 0xffff0000, v20
	v_pk_mul_f32 v[34:35], v[28:29], v[54:55]
	v_lshlrev_b32_e32 v52, 16, v21
	v_and_b32_e32 v53, 0xffff0000, v21
	v_cvt_pk_bf16_f32 v20, v34, v35
	v_pk_mul_f32 v[34:35], v[30:31], v[52:53]
	v_and_b32_e32 v61, 0xffff0000, v22
	v_cvt_pk_bf16_f32 v21, v34, v35
	v_pk_mul_f32 v[34:35], v[24:25], v[60:61]
	v_lshlrev_b32_e32 v58, 16, v23
	v_and_b32_e32 v59, 0xffff0000, v23
	v_cvt_pk_bf16_f32 v22, v34, v35
	v_pk_mul_f32 v[34:35], v[26:27], v[58:59]
	s_waitcnt lgkmcnt(0)
	v_lshlrev_b32_e32 v48, 16, v32
	v_cvt_pk_bf16_f32 v23, v34, v35
	v_and_b32_e32 v49, 0xffff0000, v32
	v_lshlrev_b32_e32 v50, 16, v33
	v_mfma_f32_16x16x32_bf16 v[36:39], v[16:19], v[20:23], 0
	ds_read_b64_tr_b16 v[22:23], v232 offset:1248
	v_and_b32_e32 v51, 0xffff0000, v33
	v_pk_mul_f32 v[20:21], v[28:29], v[48:49]
	v_pk_mul_f32 v[32:33], v[30:31], v[50:51]
	v_cvt_pk_bf16_f32 v20, v20, v21
	s_waitcnt lgkmcnt(0)
	v_lshlrev_b32_e32 v56, 16, v22
	v_and_b32_e32 v57, 0xffff0000, v22
	v_cvt_pk_bf16_f32 v21, v32, v33
	v_pk_mul_f32 v[32:33], v[24:25], v[56:57]
	v_lshlrev_b32_e32 v62, 16, v23
	v_and_b32_e32 v63, 0xffff0000, v23
	v_cvt_pk_bf16_f32 v22, v32, v33
	v_pk_mul_f32 v[32:33], v[26:27], v[62:63]
	s_lshl_b64 s[60:61], s[60:61], 15
	v_cvt_pk_bf16_f32 v23, v32, v33
	ds_read_b64_tr_b16 v[32:33], v232 offset:192
	ds_read_b64_tr_b16 v[34:35], v232 offset:1280
	v_mfma_f32_16x16x32_bf16 v[20:23], v[16:19], v[20:23], 0
	s_waitcnt lgkmcnt(1)
	v_lshlrev_b32_e32 v64, 16, v32
	v_and_b32_e32 v65, 0xffff0000, v32
	v_pk_mul_f32 v[40:41], v[28:29], v[64:65]
	v_lshlrev_b32_e32 v66, 16, v33
	v_and_b32_e32 v67, 0xffff0000, v33
	v_cvt_pk_bf16_f32 v32, v40, v41
	v_pk_mul_f32 v[40:41], v[30:31], v[66:67]
	s_waitcnt lgkmcnt(0)
	v_lshlrev_b32_e32 v68, 16, v34
	v_and_b32_e32 v69, 0xffff0000, v34
	v_cvt_pk_bf16_f32 v33, v40, v41
	v_pk_mul_f32 v[40:41], v[24:25], v[68:69]
	v_lshlrev_b32_e32 v70, 16, v35
	v_and_b32_e32 v71, 0xffff0000, v35
	v_cvt_pk_bf16_f32 v34, v40, v41
	v_pk_mul_f32 v[40:41], v[26:27], v[70:71]
	s_or_b32 s0, s0, 3
	v_cvt_pk_bf16_f32 v35, v40, v41
	ds_read_b64_tr_b16 v[40:41], v232 offset:224
	ds_read_b64_tr_b16 v[42:43], v232 offset:1312
	v_mfma_f32_16x16x32_bf16 v[32:35], v[16:19], v[32:35], 0
	s_waitcnt lgkmcnt(1)
	v_lshlrev_b32_e32 v72, 16, v40
	v_and_b32_e32 v73, 0xffff0000, v40
	v_lshlrev_b32_e32 v74, 16, v41
	v_and_b32_e32 v75, 0xffff0000, v41
	s_waitcnt lgkmcnt(0)
	v_lshlrev_b32_e32 v76, 16, v42
	v_and_b32_e32 v77, 0xffff0000, v42
	v_pk_mul_f32 v[28:29], v[28:29], v[72:73]
	v_pk_mul_f32 v[30:31], v[30:31], v[74:75]
	v_pk_mul_f32 v[24:25], v[24:25], v[76:77]
	v_lshlrev_b32_e32 v78, 16, v43
	v_and_b32_e32 v79, 0xffff0000, v43
	v_cvt_pk_bf16_f32 v28, v28, v29
	v_cvt_pk_bf16_f32 v29, v30, v31
	v_cvt_pk_bf16_f32 v30, v24, v25
	v_pk_mul_f32 v[24:25], v[26:27], v[78:79]
	s_ashr_i32 s1, s0, 31
	v_cvt_pk_bf16_f32 v31, v24, v25
	s_lshl_b64 s[0:1], s[0:1], 15
	s_cmpk_gt_i32 s31, 0xff
	v_mfma_f32_16x16x32_bf16 v[24:27], v[16:19], v[28:31], 0
	ds_read_b128 v[44:47], v231 offset:1152
	ds_read_b128 v[40:43], v231 offset:1168
	ds_read_b64_tr_b16 v[28:29], v232 offset:8832
	ds_read_b64_tr_b16 v[30:31], v232 offset:9920
	s_waitcnt lgkmcnt(1)
	v_lshlrev_b32_e32 v82, 16, v28
	v_and_b32_e32 v83, 0xffff0000, v28
	v_pk_mul_f32 v[80:81], v[44:45], v[82:83]
	s_waitcnt lgkmcnt(0)
	v_lshlrev_b32_e32 v86, 16, v30
	v_cvt_pk_bf16_f32 v28, v80, v81
	v_lshlrev_b32_e32 v80, 16, v29
	v_and_b32_e32 v81, 0xffff0000, v29
	v_pk_mul_f32 v[84:85], v[46:47], v[80:81]
	v_and_b32_e32 v87, 0xffff0000, v30
	v_cvt_pk_bf16_f32 v29, v84, v85
	v_pk_mul_f32 v[84:85], v[40:41], v[86:87]
	s_nop 0
	v_cvt_pk_bf16_f32 v30, v84, v85
	v_lshlrev_b32_e32 v84, 16, v31
	v_and_b32_e32 v85, 0xffff0000, v31
	v_pk_mul_f32 v[88:89], v[42:43], v[84:85]
	s_nop 0
	v_cvt_pk_bf16_f32 v31, v88, v89
	s_nop 1
	v_mfma_f32_16x16x32_bf16 v[28:31], v[12:15], v[28:31], v[36:39]
	s_nop 2
	ds_read_b64_tr_b16 v[36:37], v232 offset:8864
	ds_read_b64_tr_b16 v[38:39], v232 offset:9952
	s_waitcnt lgkmcnt(1)
	v_lshlrev_b32_e32 v88, 16, v36
	v_and_b32_e32 v89, 0xffff0000, v36
	v_pk_mul_f32 v[90:91], v[44:45], v[88:89]
	s_nop 0
	v_cvt_pk_bf16_f32 v36, v90, v91
	v_lshlrev_b32_e32 v90, 16, v37
	v_and_b32_e32 v91, 0xffff0000, v37
	v_pk_mul_f32 v[92:93], v[46:47], v[90:91]
	s_nop 0
	v_cvt_pk_bf16_f32 v37, v92, v93
	s_waitcnt lgkmcnt(0)
	v_lshlrev_b32_e32 v92, 16, v38
	v_and_b32_e32 v93, 0xffff0000, v38
	v_pk_mul_f32 v[94:95], v[40:41], v[92:93]
	s_nop 0
	v_cvt_pk_bf16_f32 v38, v94, v95
	v_lshlrev_b32_e32 v94, 16, v39
	v_and_b32_e32 v95, 0xffff0000, v39
	v_pk_mul_f32 v[96:97], v[42:43], v[94:95]
	s_nop 0
	v_cvt_pk_bf16_f32 v39, v96, v97
	s_nop 1
	v_mfma_f32_16x16x32_bf16 v[20:23], v[12:15], v[36:39], v[20:23]
	ds_read_b64_tr_b16 v[36:37], v232 offset:8896
	ds_read_b64_tr_b16 v[38:39], v232 offset:9984
	s_waitcnt lgkmcnt(1)
	v_lshlrev_b32_e32 v96, 16, v36
	v_and_b32_e32 v97, 0xffff0000, v36
	v_pk_mul_f32 v[98:99], v[44:45], v[96:97]
	s_nop 0
	v_cvt_pk_bf16_f32 v36, v98, v99
	v_lshlrev_b32_e32 v98, 16, v37
	v_and_b32_e32 v99, 0xffff0000, v37
	v_pk_mul_f32 v[148:149], v[46:47], v[98:99]
	s_nop 0
	v_cvt_pk_bf16_f32 v37, v148, v149
	s_waitcnt lgkmcnt(0)
	v_lshlrev_b32_e32 v148, 16, v38
	v_and_b32_e32 v149, 0xffff0000, v38
	v_pk_mul_f32 v[150:151], v[40:41], v[148:149]
	s_nop 0
	v_cvt_pk_bf16_f32 v38, v150, v151
	v_lshlrev_b32_e32 v150, 16, v39
	v_and_b32_e32 v151, 0xffff0000, v39
	v_pk_mul_f32 v[152:153], v[42:43], v[150:151]
	s_nop 0
	v_cvt_pk_bf16_f32 v39, v152, v153
	s_nop 1
	v_mfma_f32_16x16x32_bf16 v[32:35], v[12:15], v[36:39], v[32:35]
	ds_read_b64_tr_b16 v[36:37], v232 offset:8928
	ds_read_b64_tr_b16 v[38:39], v232 offset:10016
	s_waitcnt lgkmcnt(1)
; #define LAS __attribute__((address_space(3)))
; #define MFMA16(a, b, c) __builtin_amdgcn_mfma_f32_16x16x32_bf16((a), (b), (c), 0, 0, 0)
; DI unsigned pk2(float lo, float hi) { f32x2_t v = {lo, hi}; bf16x2_t b = __builtin_convertvector(v, bf16x2_t); return __builtin_bit_cast(unsigned, b); }
; DI s16x4 vtr(const LAS char* p) { return __builtin_bit_cast(s16x4, __builtin_amdgcn_ds_read_tr16_b64_v4i16((LAS s16x4*)p)); }
; DI void ssd_part1_unit(int u, const bf16* PROJ, float* DT, const bf16* H, const bf16* wdtb_l, const float* dt_bias_l, const float* cw, const float* cb, const float* a_log_l, float* STATES, float* TOT,
;                        LAS unsigned char* ldsu, int tid, int wave, int lane) {
;     ...
; #pragma unroll
;         for (int ks = 0; ks < 4; ++ks) {
;             const f32x4 w0 = *(const LAS f32x4*)(wtab + combo * 128 + 32 * ks + 8 * g), w1 = *(const LAS f32x4*)(wtab + combo * 128 + 32 * ks + 8 * g + 4);
; #pragma unroll
;             for (int pt = 0; pt < 4; ++pt) {
;                 const LAS char* xp = XS + (32 * ks + 8 * g + q) * IMG_PITCH + (hh * 64 + 16 * pt) * 2 + 8 * p;
;                 const u32x2 lo = __builtin_bit_cast(u32x2, vtr(xp)), hi = __builtin_bit_cast(u32x2, vtr(xp + 4 * IMG_PITCH));
;                 u32x4 af; af.x = pk2(bflo(lo.x) * w0[0], bfhi(lo.x) * w0[1]); af.y = pk2(bflo(lo.y) * w0[2], bfhi(lo.y) * w0[3]);
;                 af.z = pk2(bflo(hi.x) * w1[0], bfhi(hi.x) * w1[1]); af.w = pk2(bflo(hi.y) * w1[2], bfhi(hi.y) * w1[3]);
;                 acc[pt] = MFMA16(__builtin_bit_cast(bf16x8, af), bfr[ks], acc[pt]);
;             }
;         }
	v_lshlrev_b32_e32 v152, 16, v36
	v_and_b32_e32 v153, 0xffff0000, v36
	s_waitcnt lgkmcnt(0)
	v_lshlrev_b32_e32 v156, 16, v38
	v_and_b32_e32 v157, 0xffff0000, v38
	v_pk_mul_f32 v[44:45], v[44:45], v[152:153]
	v_lshlrev_b32_e32 v154, 16, v37
	v_and_b32_e32 v155, 0xffff0000, v37
	v_pk_mul_f32 v[40:41], v[40:41], v[156:157]
	v_lshlrev_b32_e32 v158, 16, v39
	v_and_b32_e32 v159, 0xffff0000, v39
	v_cvt_pk_bf16_f32 v36, v44, v45
	v_pk_mul_f32 v[44:45], v[46:47], v[154:155]
	v_cvt_pk_bf16_f32 v38, v40, v41
	v_pk_mul_f32 v[40:41], v[42:43], v[158:159]
	v_cvt_pk_bf16_f32 v37, v44, v45
	v_cvt_pk_bf16_f32 v39, v40, v41
	s_nop 1
	v_mfma_f32_16x16x32_bf16 v[24:27], v[12:15], v[36:39], v[24:27]
	ds_read_b128 v[44:47], v231 offset:1280
	ds_read_b128 v[40:43], v231 offset:1296
	ds_read_b64_tr_b16 v[36:37], v232 offset:17536
	ds_read_b64_tr_b16 v[38:39], v232 offset:18624
	s_waitcnt lgkmcnt(1)
	v_lshlrev_b32_e32 v162, 16, v36
	v_and_b32_e32 v163, 0xffff0000, v36
	v_pk_mul_f32 v[160:161], v[44:45], v[162:163]
	s_waitcnt lgkmcnt(0)
	v_lshlrev_b32_e32 v166, 16, v38
	v_cvt_pk_bf16_f32 v36, v160, v161
	v_lshlrev_b32_e32 v160, 16, v37
	v_and_b32_e32 v161, 0xffff0000, v37
	v_pk_mul_f32 v[164:165], v[46:47], v[160:161]
	v_and_b32_e32 v167, 0xffff0000, v38
	v_cvt_pk_bf16_f32 v37, v164, v165
	v_pk_mul_f32 v[164:165], v[40:41], v[166:167]
	s_nop 0
	v_cvt_pk_bf16_f32 v38, v164, v165
	v_lshlrev_b32_e32 v164, 16, v39
	v_and_b32_e32 v165, 0xffff0000, v39
	v_pk_mul_f32 v[168:169], v[42:43], v[164:165]
	s_nop 0
	v_cvt_pk_bf16_f32 v39, v168, v169
	s_nop 1
	v_mfma_f32_16x16x32_bf16 v[28:31], v[8:11], v[36:39], v[28:31]
	ds_read_b64_tr_b16 v[36:37], v232 offset:17568
	ds_read_b64_tr_b16 v[38:39], v232 offset:18656
	s_waitcnt lgkmcnt(1)
	v_lshlrev_b32_e32 v168, 16, v36
	v_and_b32_e32 v169, 0xffff0000, v36
	v_pk_mul_f32 v[170:171], v[44:45], v[168:169]
	s_nop 0
	v_cvt_pk_bf16_f32 v36, v170, v171
	v_lshlrev_b32_e32 v170, 16, v37
	v_and_b32_e32 v171, 0xffff0000, v37
	v_pk_mul_f32 v[172:173], v[46:47], v[170:171]
	s_nop 0
	v_cvt_pk_bf16_f32 v37, v172, v173
	s_waitcnt lgkmcnt(0)
	v_lshlrev_b32_e32 v172, 16, v38
	v_and_b32_e32 v173, 0xffff0000, v38
	v_pk_mul_f32 v[174:175], v[40:41], v[172:173]
	s_nop 0
	v_cvt_pk_bf16_f32 v38, v174, v175
	v_lshlrev_b32_e32 v174, 16, v39
	v_and_b32_e32 v175, 0xffff0000, v39
	v_pk_mul_f32 v[176:177], v[42:43], v[174:175]
	s_nop 0
	v_cvt_pk_bf16_f32 v39, v176, v177
	s_nop 1
	v_mfma_f32_16x16x32_bf16 v[36:39], v[8:11], v[36:39], v[20:23]
	s_nop 2
	ds_read_b64_tr_b16 v[20:21], v232 offset:17600
	ds_read_b64_tr_b16 v[22:23], v232 offset:18688
	s_waitcnt lgkmcnt(1)
	v_lshlrev_b32_e32 v176, 16, v20
	v_and_b32_e32 v177, 0xffff0000, v20
	v_pk_mul_f32 v[178:179], v[44:45], v[176:177]
	s_nop 0
	v_cvt_pk_bf16_f32 v20, v178, v179
	v_lshlrev_b32_e32 v178, 16, v21
	v_and_b32_e32 v179, 0xffff0000, v21
	v_pk_mul_f32 v[180:181], v[46:47], v[178:179]
	s_nop 0
	v_cvt_pk_bf16_f32 v21, v180, v181
	s_waitcnt lgkmcnt(0)
	v_lshlrev_b32_e32 v180, 16, v22
	v_and_b32_e32 v181, 0xffff0000, v22
	v_pk_mul_f32 v[182:183], v[40:41], v[180:181]
	s_nop 0
	v_cvt_pk_bf16_f32 v22, v182, v183
	v_lshlrev_b32_e32 v182, 16, v23
	v_and_b32_e32 v183, 0xffff0000, v23
	v_pk_mul_f32 v[184:185], v[42:43], v[182:183]
	s_nop 0
	v_cvt_pk_bf16_f32 v23, v184, v185
	s_nop 1
	v_mfma_f32_16x16x32_bf16 v[32:35], v[8:11], v[20:23], v[32:35]
	ds_read_b64_tr_b16 v[20:21], v232 offset:17632
	ds_read_b64_tr_b16 v[22:23], v232 offset:18720
	s_waitcnt lgkmcnt(1)
	v_lshlrev_b32_e32 v184, 16, v20
	v_and_b32_e32 v185, 0xffff0000, v20
	v_pk_mul_f32 v[44:45], v[44:45], v[184:185]
	s_waitcnt lgkmcnt(0)
	v_lshlrev_b32_e32 v186, 16, v23
	v_cvt_pk_bf16_f32 v20, v44, v45
	v_lshlrev_b32_e32 v44, 16, v21
	v_and_b32_e32 v45, 0xffff0000, v21
	v_pk_mul_f32 v[46:47], v[46:47], v[44:45]
	v_and_b32_e32 v187, 0xffff0000, v23
	v_cvt_pk_bf16_f32 v21, v46, v47
	v_lshlrev_b32_e32 v46, 16, v22
	v_and_b32_e32 v47, 0xffff0000, v22
	v_pk_mul_f32 v[40:41], v[40:41], v[46:47]
	s_nop 0
	v_cvt_pk_bf16_f32 v22, v40, v41
	v_pk_mul_f32 v[40:41], v[42:43], v[186:187]
	s_nop 0
	v_cvt_pk_bf16_f32 v23, v40, v41
	s_nop 1
	v_mfma_f32_16x16x32_bf16 v[20:23], v[8:11], v[20:23], v[24:27]
	ds_read_b128 v[40:43], v231 offset:1408
	s_nop 1
	ds_read_b128 v[24:27], v231 offset:1424
	ds_read_b64_tr_b16 v[198:199], v232 offset:26240
	ds_read_b64_tr_b16 v[202:203], v232 offset:27328
	s_waitcnt lgkmcnt(1)
	v_lshlrev_b32_e32 v200, 16, v198
	v_and_b32_e32 v201, 0xffff0000, v198
	v_pk_mul_f32 v[204:205], v[40:41], v[200:201]
	v_lshlrev_b32_e32 v198, 16, v199
	v_and_b32_e32 v199, 0xffff0000, v199
	v_cvt_pk_bf16_f32 v206, v204, v205
	v_pk_mul_f32 v[204:205], v[42:43], v[198:199]
	s_nop 0
	v_cvt_pk_bf16_f32 v207, v204, v205
	s_waitcnt lgkmcnt(0)
	v_lshlrev_b32_e32 v204, 16, v202
	v_and_b32_e32 v205, 0xffff0000, v202
	v_lshlrev_b32_e32 v202, 16, v203
	v_and_b32_e32 v203, 0xffff0000, v203
	v_pk_mul_f32 v[208:209], v[24:25], v[204:205]
	v_pk_mul_f32 v[210:211], v[26:27], v[202:203]
	v_cvt_pk_bf16_f32 v208, v208, v209
	v_cvt_pk_bf16_f32 v209, v210, v211
	s_nop 1
	v_mfma_f32_16x16x32_bf16 v[28:31], v[4:7], v[206:209], v[28:31]
	ds_read_b64_tr_b16 v[208:209], v232 offset:26272
	ds_read_b64_tr_b16 v[212:213], v232 offset:27360
	s_waitcnt lgkmcnt(1)
	v_lshlrev_b32_e32 v206, 16, v208
	v_and_b32_e32 v207, 0xffff0000, v208
	v_pk_mul_f32 v[210:211], v[40:41], v[206:207]
	v_lshlrev_b32_e32 v208, 16, v209
	v_and_b32_e32 v209, 0xffff0000, v209
	v_cvt_pk_bf16_f32 v214, v210, v211
	v_pk_mul_f32 v[210:211], v[42:43], v[208:209]
	s_nop 0
	v_cvt_pk_bf16_f32 v215, v210, v211
	s_waitcnt lgkmcnt(0)
; #define MFMA16(a, b, c) __builtin_amdgcn_mfma_f32_16x16x32_bf16((a), (b), (c), 0, 0, 0)
; DI unsigned pk2(float lo, float hi) { f32x2_t v = {lo, hi}; bf16x2_t b = __builtin_convertvector(v, bf16x2_t); return __builtin_bit_cast(unsigned, b); }
; DI void ssd_part1_unit(int u, const bf16* PROJ, float* DT, const bf16* H, const bf16* wdtb_l, const float* dt_bias_l, const float* cw, const float* cb, const float* a_log_l, float* STATES, float* TOT,
;                        LAS unsigned char* ldsu, int tid, int wave, int lane) {
;     ...
;                 u32x4 af; af.x = pk2(bflo(lo.x) * w0[0], bfhi(lo.x) * w0[1]); af.y = pk2(bflo(lo.y) * w0[2], bfhi(lo.y) * w0[3]);
;                 af.z = pk2(bflo(hi.x) * w1[0], bfhi(hi.x) * w1[1]); af.w = pk2(bflo(hi.y) * w1[2], bfhi(hi.y) * w1[3]);
;                 acc[pt] = MFMA16(__builtin_bit_cast(bf16x8, af), bfr[ks], acc[pt]);
;             }
;         }
;         float* sb = STATES + ((size_t)(((b * 16 + c) * 4 + h) * 2 + dir) * 64) * 128;
; #pragma unroll
;         for (int pt = 0; pt < 4; ++pt)
; #pragma unroll
;             for (int i = 0; i < 4; ++i) sb[(size_t)(16 * pt + 4 * g + i) * 128 + 16 * wave + r] = acc[pt][i];
	v_lshlrev_b32_e32 v210, 16, v212
	v_and_b32_e32 v211, 0xffff0000, v212
	v_lshlrev_b32_e32 v212, 16, v213
	v_and_b32_e32 v213, 0xffff0000, v213
	v_pk_mul_f32 v[216:217], v[24:25], v[210:211]
	v_pk_mul_f32 v[218:219], v[26:27], v[212:213]
	v_cvt_pk_bf16_f32 v216, v216, v217
	v_cvt_pk_bf16_f32 v217, v218, v219
	s_nop 1
	v_mfma_f32_16x16x32_bf16 v[36:39], v[4:7], v[214:217], v[36:39]
	ds_read_b64_tr_b16 v[216:217], v232 offset:26304
	ds_read_b64_tr_b16 v[220:221], v232 offset:27392
	s_waitcnt lgkmcnt(1)
	v_lshlrev_b32_e32 v214, 16, v216
	v_and_b32_e32 v215, 0xffff0000, v216
	v_pk_mul_f32 v[218:219], v[40:41], v[214:215]
	v_lshlrev_b32_e32 v216, 16, v217
	v_and_b32_e32 v217, 0xffff0000, v217
	v_cvt_pk_bf16_f32 v248, v218, v219
	v_pk_mul_f32 v[218:219], v[42:43], v[216:217]
	s_nop 0
	v_cvt_pk_bf16_f32 v249, v218, v219
	s_waitcnt lgkmcnt(0)
	v_lshlrev_b32_e32 v218, 16, v220
	v_and_b32_e32 v219, 0xffff0000, v220
	v_pk_mul_f32 v[222:223], v[24:25], v[218:219]
	v_lshlrev_b32_e32 v220, 16, v221
	v_and_b32_e32 v221, 0xffff0000, v221
	v_cvt_pk_bf16_f32 v250, v222, v223
	v_pk_mul_f32 v[222:223], v[26:27], v[220:221]
	s_nop 0
	v_cvt_pk_bf16_f32 v251, v222, v223
	s_nop 1
	v_mfma_f32_16x16x32_bf16 v[32:35], v[4:7], v[248:251], v[32:35]
	ds_read_b64_tr_b16 v[248:249], v232 offset:26336
	ds_read_b64_tr_b16 v[250:251], v232 offset:27424
	s_waitcnt lgkmcnt(1)
	v_lshlrev_b32_e32 v222, 16, v248
	v_and_b32_e32 v223, 0xffff0000, v248
	v_pk_mul_f32 v[40:41], v[40:41], v[222:223]
	s_nop 0
	v_cvt_pk_bf16_f32 v248, v40, v41
	v_lshlrev_b32_e32 v40, 16, v249
	v_and_b32_e32 v41, 0xffff0000, v249
	v_pk_mul_f32 v[42:43], v[42:43], v[40:41]
	s_nop 0
	v_cvt_pk_bf16_f32 v249, v42, v43
	s_waitcnt lgkmcnt(0)
	v_lshlrev_b32_e32 v42, 16, v250
	v_and_b32_e32 v43, 0xffff0000, v250
	v_pk_mul_f32 v[24:25], v[24:25], v[42:43]
	s_nop 0
	v_cvt_pk_bf16_f32 v250, v24, v25
	v_lshlrev_b32_e32 v24, 16, v251
	v_and_b32_e32 v25, 0xffff0000, v251
	v_pk_mul_f32 v[26:27], v[26:27], v[24:25]
	s_nop 0
	v_cvt_pk_bf16_f32 v251, v26, v27
	v_lshl_add_u64 v[26:27], v[112:113], 0, s[60:61]
	s_nop 0
	v_mfma_f32_16x16x32_bf16 v[20:23], v[4:7], v[248:251], v[20:23]
	s_nop 7
	v_lshl_add_u64 v[248:249], v[26:27], 0, v[124:125]
	global_store_dwordx4 v[248:249], v[28:31], off
	v_lshl_add_u64 v[248:249], v[26:27], 0, v[126:127]
	global_store_dwordx4 v[248:249], v[36:39], off
	v_lshl_add_u64 v[248:249], v[26:27], 0, v[128:129]
	global_store_dwordx4 v[248:249], v[32:35], off
	v_lshl_add_u64 v[248:249], v[26:27], 0, v[130:131]
	global_store_dwordx4 v[248:249], v[20:23], off
	s_nop 1
	ds_read_b128 v[20:23], v231 offset:1536
	ds_read_b128 v[26:29], v231 offset:1552
	s_waitcnt lgkmcnt(1)
	v_pk_mul_f32 v[30:31], v[20:21], v[54:55]
	v_pk_mul_f32 v[32:33], v[22:23], v[52:53]
	v_cvt_pk_bf16_f32 v30, v30, v31
	v_cvt_pk_bf16_f32 v31, v32, v33
	s_waitcnt lgkmcnt(0)
	v_pk_mul_f32 v[32:33], v[26:27], v[60:61]
	v_pk_mul_f32 v[34:35], v[28:29], v[58:59]
	v_cvt_pk_bf16_f32 v32, v32, v33
	v_cvt_pk_bf16_f32 v33, v34, v35
	v_pk_mul_f32 v[34:35], v[20:21], v[48:49]
	v_pk_mul_f32 v[36:37], v[22:23], v[50:51]
	v_cvt_pk_bf16_f32 v34, v34, v35
	v_cvt_pk_bf16_f32 v35, v36, v37
	v_pk_mul_f32 v[36:37], v[26:27], v[56:57]
	v_pk_mul_f32 v[38:39], v[28:29], v[62:63]
	v_cvt_pk_bf16_f32 v36, v36, v37
	v_cvt_pk_bf16_f32 v37, v38, v39
	v_pk_mul_f32 v[38:39], v[20:21], v[64:65]
	v_pk_mul_f32 v[20:21], v[20:21], v[72:73]
	v_cvt_pk_bf16_f32 v48, v38, v39
	v_pk_mul_f32 v[38:39], v[22:23], v[66:67]
	v_pk_mul_f32 v[22:23], v[22:23], v[74:75]
	v_cvt_pk_bf16_f32 v49, v38, v39
	v_pk_mul_f32 v[38:39], v[26:27], v[68:69]
	v_cvt_pk_bf16_f32 v20, v20, v21
	v_cvt_pk_bf16_f32 v50, v38, v39
	v_pk_mul_f32 v[38:39], v[28:29], v[70:71]
	v_cvt_pk_bf16_f32 v21, v22, v23
	v_pk_mul_f32 v[22:23], v[26:27], v[76:77]
	v_pk_mul_f32 v[26:27], v[28:29], v[78:79]
	v_cvt_pk_bf16_f32 v51, v38, v39
	v_cvt_pk_bf16_f32 v22, v22, v23
	v_cvt_pk_bf16_f32 v23, v26, v27
	v_mfma_f32_16x16x32_bf16 v[30:33], v[16:19], v[30:33], 0
	v_mfma_f32_16x16x32_bf16 v[34:37], v[16:19], v[34:37], 0
	v_mfma_f32_16x16x32_bf16 v[48:51], v[16:19], v[48:51], 0
	v_mfma_f32_16x16x32_bf16 v[16:19], v[16:19], v[20:23], 0
	ds_read_b128 v[20:23], v231 offset:1664
	ds_read_b128 v[26:29], v231 offset:1680
	s_waitcnt lgkmcnt(1)
	v_pk_mul_f32 v[38:39], v[20:21], v[82:83]
	s_nop 0
	v_cvt_pk_bf16_f32 v52, v38, v39
	v_pk_mul_f32 v[38:39], v[22:23], v[80:81]
	s_nop 0
	v_cvt_pk_bf16_f32 v53, v38, v39
	s_waitcnt lgkmcnt(0)
; #define LAS __attribute__((address_space(3)))
; #define MFMA16(a, b, c) __builtin_amdgcn_mfma_f32_16x16x32_bf16((a), (b), (c), 0, 0, 0)
; DI unsigned pk2(float lo, float hi) { f32x2_t v = {lo, hi}; bf16x2_t b = __builtin_convertvector(v, bf16x2_t); return __builtin_bit_cast(unsigned, b); }
; DI s16x4 vtr(const LAS char* p) { return __builtin_bit_cast(s16x4, __builtin_amdgcn_ds_read_tr16_b64_v4i16((LAS s16x4*)p)); }
; DI void ssd_part1_unit(int u, const bf16* PROJ, float* DT, const bf16* H, const bf16* wdtb_l, const float* dt_bias_l, const float* cw, const float* cb, const float* a_log_l, float* STATES, float* TOT,
;                        LAS unsigned char* ldsu, int tid, int wave, int lane) {
;     ...
;         for (int ks = 0; ks < 4; ++ks) {
;             const f32x4 w0 = *(const LAS f32x4*)(wtab + combo * 128 + 32 * ks + 8 * g), w1 = *(const LAS f32x4*)(wtab + combo * 128 + 32 * ks + 8 * g + 4);
; #pragma unroll
;             for (int pt = 0; pt < 4; ++pt) {
;                 const LAS char* xp = XS + (32 * ks + 8 * g + q) * IMG_PITCH + (hh * 64 + 16 * pt) * 2 + 8 * p;
;                 const u32x2 lo = __builtin_bit_cast(u32x2, vtr(xp)), hi = __builtin_bit_cast(u32x2, vtr(xp + 4 * IMG_PITCH));
;                 u32x4 af; af.x = pk2(bflo(lo.x) * w0[0], bfhi(lo.x) * w0[1]); af.y = pk2(bflo(lo.y) * w0[2], bfhi(lo.y) * w0[3]);
;                 af.z = pk2(bflo(hi.x) * w1[0], bfhi(hi.x) * w1[1]); af.w = pk2(bflo(hi.y) * w1[2], bfhi(hi.y) * w1[3]);
;                 acc[pt] = MFMA16(__builtin_bit_cast(bf16x8, af), bfr[ks], acc[pt]);
;             }
;         }
;         float* sb = STATES + ((size_t)(((b * 16 + c) * 4 + h) * 2 + dir) * 64) * 128;
; #pragma unroll
;         for (int pt = 0; pt < 4; ++pt)
; #pragma unroll
;             for (int i = 0; i < 4; ++i) sb[(size_t)(16 * pt + 4 * g + i) * 128 + 16 * wave + r] = acc[pt][i];
;     }
	v_pk_mul_f32 v[38:39], v[26:27], v[86:87]
	s_nop 0
	v_cvt_pk_bf16_f32 v54, v38, v39
	v_pk_mul_f32 v[38:39], v[28:29], v[84:85]
	s_nop 0
	v_cvt_pk_bf16_f32 v55, v38, v39
	v_pk_mul_f32 v[38:39], v[20:21], v[88:89]
	s_nop 0
	v_mfma_f32_16x16x32_bf16 v[30:33], v[12:15], v[52:55], v[30:33]
	v_cvt_pk_bf16_f32 v52, v38, v39
	v_pk_mul_f32 v[38:39], v[22:23], v[90:91]
	s_nop 0
	v_cvt_pk_bf16_f32 v53, v38, v39
	v_pk_mul_f32 v[38:39], v[26:27], v[92:93]
	s_nop 0
	v_cvt_pk_bf16_f32 v54, v38, v39
	v_pk_mul_f32 v[38:39], v[28:29], v[94:95]
	s_nop 0
	v_cvt_pk_bf16_f32 v55, v38, v39
	v_pk_mul_f32 v[38:39], v[20:21], v[96:97]
	v_pk_mul_f32 v[20:21], v[20:21], v[152:153]
	v_mfma_f32_16x16x32_bf16 v[34:37], v[12:15], v[52:55], v[34:37]
	v_cvt_pk_bf16_f32 v52, v38, v39
	v_pk_mul_f32 v[38:39], v[22:23], v[98:99]
	v_pk_mul_f32 v[22:23], v[22:23], v[154:155]
	v_cvt_pk_bf16_f32 v53, v38, v39
	v_pk_mul_f32 v[38:39], v[26:27], v[148:149]
	v_cvt_pk_bf16_f32 v20, v20, v21
	v_cvt_pk_bf16_f32 v54, v38, v39
	v_pk_mul_f32 v[38:39], v[28:29], v[150:151]
	v_cvt_pk_bf16_f32 v21, v22, v23
	v_pk_mul_f32 v[22:23], v[26:27], v[156:157]
	v_pk_mul_f32 v[26:27], v[28:29], v[158:159]
	v_cvt_pk_bf16_f32 v55, v38, v39
	v_cvt_pk_bf16_f32 v22, v22, v23
	v_cvt_pk_bf16_f32 v23, v26, v27
	v_mfma_f32_16x16x32_bf16 v[48:51], v[12:15], v[52:55], v[48:51]
	s_nop 0
	v_mfma_f32_16x16x32_bf16 v[12:15], v[12:15], v[20:23], v[16:19]
	s_nop 2
	ds_read_b128 v[16:19], v231 offset:1792
	ds_read_b128 v[20:23], v231 offset:1808
	s_waitcnt lgkmcnt(1)
	v_pk_mul_f32 v[26:27], v[16:17], v[162:163]
	v_pk_mul_f32 v[28:29], v[18:19], v[160:161]
	v_cvt_pk_bf16_f32 v26, v26, v27
	v_cvt_pk_bf16_f32 v27, v28, v29
	s_waitcnt lgkmcnt(0)
	v_pk_mul_f32 v[28:29], v[20:21], v[166:167]
	v_pk_mul_f32 v[38:39], v[22:23], v[164:165]
	v_cvt_pk_bf16_f32 v28, v28, v29
	v_cvt_pk_bf16_f32 v29, v38, v39
	v_pk_mul_f32 v[38:39], v[22:23], v[174:175]
	s_nop 0
	v_mfma_f32_16x16x32_bf16 v[26:29], v[8:11], v[26:29], v[30:33]
	s_nop 2
	v_mul_f32_e64 v30, v16, v168
	v_mul_f32_e64 v31, v17, v169
	v_pk_mul_f32 v[32:33], v[18:19], v[170:171]
	v_cvt_pk_bf16_f32 v30, v30, v31
	v_cvt_pk_bf16_f32 v31, v32, v33
	v_pk_mul_f32 v[32:33], v[20:21], v[172:173]
	s_nop 0
	v_cvt_pk_bf16_f32 v32, v32, v33
	v_cvt_pk_bf16_f32 v33, v38, v39
	v_pk_mul_f32 v[38:39], v[22:23], v[182:183]
	s_nop 0
	v_mfma_f32_16x16x32_bf16 v[30:33], v[8:11], v[30:33], v[34:37]
	s_nop 2
	v_mul_f32_e64 v34, v16, v176
	v_mul_f32_e64 v35, v17, v177
	v_pk_mul_f32 v[36:37], v[18:19], v[178:179]
	v_pk_mul_f32 v[16:17], v[16:17], v[184:185]
	v_pk_mul_f32 v[18:19], v[18:19], v[44:45]
	v_cvt_pk_bf16_f32 v34, v34, v35
	v_cvt_pk_bf16_f32 v35, v36, v37
	v_pk_mul_f32 v[36:37], v[20:21], v[180:181]
	v_cvt_pk_bf16_f32 v16, v16, v17
	v_cvt_pk_bf16_f32 v17, v18, v19
	v_pk_mul_f32 v[18:19], v[20:21], v[46:47]
	v_pk_mul_f32 v[20:21], v[22:23], v[186:187]
	v_cvt_pk_bf16_f32 v36, v36, v37
	v_cvt_pk_bf16_f32 v37, v38, v39
	v_cvt_pk_bf16_f32 v18, v18, v19
	v_cvt_pk_bf16_f32 v19, v20, v21
	v_mfma_f32_16x16x32_bf16 v[34:37], v[8:11], v[34:37], v[48:51]
	s_nop 0
	v_mfma_f32_16x16x32_bf16 v[8:11], v[8:11], v[16:19], v[12:15]
	s_nop 2
	ds_read_b128 v[12:15], v231 offset:1920
	ds_read_b128 v[16:19], v231 offset:1936
	s_waitcnt lgkmcnt(1)
	v_pk_mul_f32 v[20:21], v[12:13], v[200:201]
	v_pk_mul_f32 v[22:23], v[14:15], v[198:199]
	v_cvt_pk_bf16_f32 v20, v20, v21
	v_cvt_pk_bf16_f32 v21, v22, v23
	s_waitcnt lgkmcnt(0)
	v_pk_mul_f32 v[22:23], v[16:17], v[204:205]
	v_pk_mul_f32 v[38:39], v[18:19], v[202:203]
	v_cvt_pk_bf16_f32 v22, v22, v23
	v_cvt_pk_bf16_f32 v23, v38, v39
	v_pk_mul_f32 v[38:39], v[18:19], v[212:213]
	s_nop 0
	v_mfma_f32_16x16x32_bf16 v[20:23], v[4:7], v[20:23], v[26:29]
	s_nop 2
	v_mul_f32_e64 v26, v12, v206
	v_mul_f32_e64 v27, v13, v207
	v_pk_mul_f32 v[28:29], v[14:15], v[208:209]
	v_cvt_pk_bf16_f32 v26, v26, v27
	v_cvt_pk_bf16_f32 v27, v28, v29
	v_pk_mul_f32 v[28:29], v[16:17], v[210:211]
	s_nop 0
	v_cvt_pk_bf16_f32 v28, v28, v29
	v_cvt_pk_bf16_f32 v29, v38, v39
	v_pk_mul_f32 v[38:39], v[18:19], v[220:221]
	s_nop 0
	v_mfma_f32_16x16x32_bf16 v[26:29], v[4:7], v[26:29], v[30:33]
	s_nop 2
	v_mul_f32_e64 v30, v12, v214
	v_mul_f32_e64 v31, v13, v215
	v_pk_mul_f32 v[32:33], v[14:15], v[216:217]
	v_pk_mul_f32 v[12:13], v[12:13], v[222:223]
	v_pk_mul_f32 v[14:15], v[14:15], v[40:41]
	v_cvt_pk_bf16_f32 v30, v30, v31
	v_cvt_pk_bf16_f32 v31, v32, v33
	v_pk_mul_f32 v[32:33], v[16:17], v[218:219]
	v_cvt_pk_bf16_f32 v12, v12, v13
	v_cvt_pk_bf16_f32 v13, v14, v15
	v_pk_mul_f32 v[14:15], v[16:17], v[42:43]
	v_pk_mul_f32 v[16:17], v[18:19], v[24:25]
	v_cvt_pk_bf16_f32 v32, v32, v33
	v_cvt_pk_bf16_f32 v33, v38, v39
	v_cvt_pk_bf16_f32 v14, v14, v15
	v_cvt_pk_bf16_f32 v15, v16, v17
	v_mfma_f32_16x16x32_bf16 v[30:33], v[4:7], v[30:33], v[34:37]
	s_nop 0
	v_mfma_f32_16x16x32_bf16 v[4:7], v[4:7], v[12:15], v[8:11]
	s_nop 2
	v_lshl_add_u64 v[8:9], v[112:113], 0, s[0:1]
	s_nop 7
	v_lshl_add_u64 v[10:11], v[8:9], 0, v[124:125]
	global_store_dwordx4 v[10:11], v[20:23], off
	v_lshl_add_u64 v[10:11], v[8:9], 0, v[126:127]
	global_store_dwordx4 v[10:11], v[26:29], off
	v_lshl_add_u64 v[10:11], v[8:9], 0, v[128:129]
	global_store_dwordx4 v[10:11], v[30:33], off
	v_lshl_add_u64 v[10:11], v[8:9], 0, v[130:131]
	global_store_dwordx4 v[10:11], v[4:7], off
	s_nop 1
	s_cbranch_scc1 .LBB0_356
